# speedup vs baseline: 1.0332x; 1.0251x over previous
.LBB0_184:
	s_bfe_u32 s0, s13, 0x100005
	s_mulk_i32 s0, 0x2493
	s_lshr_b32 s0, s0, 16
	s_and_b32 s0, s0, 0xffff
	s_mul_i32 s2, s0, 0xff20
	s_add_i32 s3, s2, s13
	s_sext_i32_i16 s2, s3
	s_mulk_i32 s2, 0x4925
	s_lshr_b32 s4, s2, 31
	s_ashr_i32 s2, s2, 17
	s_add_i32 s2, s2, s4
	s_mul_i32 s4, s2, 7
	s_lshl_b32 s2, s2, 10
	s_or_b32 s2, s2, s14
	v_or_b32_e32 v2, s2, v1
	v_ashrrev_i32_e32 v3, 31, v2
	v_lshlrev_b64 v[2:3], 11, v[2:3]
	s_sub_i32 s3, s3, s4
	s_mul_i32 s0, s0, 7
	v_lshl_add_u64 v[104:105], v[100:101], 0, v[2:3]
	s_sext_i32_i16 s3, s3
	s_add_i32 s0, s0, s3
	s_lshl_b32 s3, s0, 7
	v_or_b32_e32 v18, s3, v1
	v_ashrrev_i32_e32 v19, 31, v18
	v_lshlrev_b64 v[18:19], 11, v[18:19]
	v_lshl_add_u64 v[108:109], v[102:103], 0, v[18:19]
	s_mov_b32 s4, -2
	s_mov_b32 s5, s1
	v_mov_b32_e32 v26, 0
	v_mov_b32_e32 v27, v99
	v_mov_b32_e32 v28, v99
	v_mov_b32_e32 v29, v99
	v_mov_b32_e32 v46, 0
	v_mov_b32_e32 v47, v99
	v_mov_b32_e32 v48, v99
	v_mov_b32_e32 v49, v99
	v_mov_b32_e32 v62, 0
	v_mov_b32_e32 v63, v99
	v_mov_b32_e32 v64, v99
	v_mov_b32_e32 v65, v99
	v_mov_b32_e32 v78, 0
	v_mov_b32_e32 v79, v99
	v_mov_b32_e32 v80, v99
	v_mov_b32_e32 v81, v99
	v_mov_b32_e32 v82, 0
	v_mov_b32_e32 v83, v99
	v_mov_b32_e32 v84, v99
	v_mov_b32_e32 v85, v99
	v_mov_b32_e32 v86, 0
	v_mov_b32_e32 v87, v99
	v_mov_b32_e32 v88, v99
	v_mov_b32_e32 v89, v99
	v_mov_b32_e32 v90, 0
	v_mov_b32_e32 v91, v99
	v_mov_b32_e32 v92, v99
	v_mov_b32_e32 v93, v99
	v_mov_b32_e32 v94, 0
	v_mov_b32_e32 v95, v99
	v_mov_b32_e32 v96, v99
	v_mov_b32_e32 v97, v99
	v_mov_b32_e32 v38, 0
	v_mov_b32_e32 v39, v99
	v_mov_b32_e32 v40, v99
	v_mov_b32_e32 v41, v99
	v_mov_b32_e32 v30, 0
	v_mov_b32_e32 v31, v99
	v_mov_b32_e32 v32, v99
	v_mov_b32_e32 v33, v99
	v_mov_b32_e32 v22, 0
	v_mov_b32_e32 v23, v99
	v_mov_b32_e32 v24, v99
	v_mov_b32_e32 v25, v99
	v_mov_b32_e32 v18, 0
	v_mov_b32_e32 v19, v99
	v_mov_b32_e32 v20, v99
	v_mov_b32_e32 v21, v99
	v_mov_b32_e32 v14, 0
	v_mov_b32_e32 v15, v99
	v_mov_b32_e32 v16, v99
	v_mov_b32_e32 v17, v99
	v_mov_b32_e32 v10, 0
	v_mov_b32_e32 v11, v99
	v_mov_b32_e32 v12, v99
	v_mov_b32_e32 v13, v99
	v_mov_b32_e32 v6, 0
	v_mov_b32_e32 v7, v99
	v_mov_b32_e32 v8, v99
	v_mov_b32_e32 v9, v99
	v_mov_b32_e32 v2, 0
	v_mov_b32_e32 v3, v99
	v_mov_b32_e32 v4, v99
	v_mov_b32_e32 v5, v99
	v_and_b32_e32 v181, 7, v106
	v_bfe_u32 v180, v106, 3, 3
	v_xor_b32_e32 v180, v181, v180
	v_sub_u32_e32 v180, v180, v181
	v_lshlrev_b32_e32 v180, 4, v180
	v_ashrrev_i32_e32 v181, 31, v180
	v_lshrrev_b32_e32 v186, 6, v106
	v_mov_b32_e32 v187, 0x110
	v_lshl_add_u32 v186, v186, 10, v187
	v_lshl_add_u64 v[188:189], v[104:105], 0, v[180:181]
	v_lshl_add_u64 v[196:197], v[108:109], 0, v[180:181]
	v_readfirstlane_b32 s6, v186
	v_add_co_u32_e32 v190, vcc, s15, v188
	v_addc_co_u32_e32 v191, vcc, 0, v189, vcc
	v_add_co_u32_e32 v192, vcc, s16, v188
	v_addc_co_u32_e32 v193, vcc, 0, v189, vcc
	v_add_co_u32_e32 v194, vcc, s17, v188
	v_addc_co_u32_e32 v195, vcc, 0, v189, vcc
	v_add_co_u32_e32 v198, vcc, s15, v196
	v_addc_co_u32_e32 v199, vcc, 0, v197, vcc
	v_add_co_u32_e32 v200, vcc, s16, v196
	v_addc_co_u32_e32 v201, vcc, 0, v197, vcc
	v_add_co_u32_e32 v202, vcc, s17, v196
	v_addc_co_u32_e32 v203, vcc, 0, v197, vcc
	s_add_u32 m0, s6, 0x0
	s_nop 0
	global_load_lds_dwordx4 v[188:189], off
	s_add_u32 m0, s6, 0x1000
	s_nop 0
	global_load_lds_dwordx4 v[190:191], off
	s_add_u32 m0, s6, 0x2000
	s_nop 0
	global_load_lds_dwordx4 v[192:193], off
	s_add_u32 m0, s6, 0x3000
	s_nop 0
	global_load_lds_dwordx4 v[194:195], off
	s_add_u32 m0, s6, 0x4000
	s_nop 0
	global_load_lds_dwordx4 v[196:197], off
	s_add_u32 m0, s6, 0x5000
	s_nop 0
	global_load_lds_dwordx4 v[198:199], off
	s_add_u32 m0, s6, 0x6000
	s_nop 0
	global_load_lds_dwordx4 v[200:201], off
	s_add_u32 m0, s6, 0x7000
	s_nop 0
	global_load_lds_dwordx4 v[202:203], off
	s_mov_b32 s5, 0
	s_mov_b32 s4, -2
	s_waitcnt vmcnt(0)
	s_barrier
.Lglds_2829:
	s_add_i32 s0, s5, 0x40
	s_lshl_b32 s0, s0, 1
	s_add_u32 m0, s6, 0x8000
	v_lshl_add_u64 v[204:205], v[188:189], 0, s[0:1]
	global_load_lds_dwordx4 v[204:205], off
	s_add_u32 m0, s6, 0x9000
	v_lshl_add_u64 v[206:207], v[190:191], 0, s[0:1]
	global_load_lds_dwordx4 v[206:207], off
	s_add_u32 m0, s6, 0xa000
	v_lshl_add_u64 v[204:205], v[192:193], 0, s[0:1]
	global_load_lds_dwordx4 v[204:205], off
	s_add_u32 m0, s6, 0xb000
	v_lshl_add_u64 v[206:207], v[194:195], 0, s[0:1]
	global_load_lds_dwordx4 v[206:207], off
	s_add_u32 m0, s6, 0xc000
	v_lshl_add_u64 v[204:205], v[196:197], 0, s[0:1]
	global_load_lds_dwordx4 v[204:205], off
	s_add_u32 m0, s6, 0xd000
	v_lshl_add_u64 v[206:207], v[198:199], 0, s[0:1]
	global_load_lds_dwordx4 v[206:207], off
	s_add_u32 m0, s6, 0xe000
	v_lshl_add_u64 v[204:205], v[200:201], 0, s[0:1]
	global_load_lds_dwordx4 v[204:205], off
	s_add_u32 m0, s6, 0xf000
	v_lshl_add_u64 v[206:207], v[202:203], 0, s[0:1]
	global_load_lds_dwordx4 v[206:207], off
	s_setprio 1
	ds_read_b128 v[154:157], v112 offset:16384
	ds_read_b128 v[158:161], v112 offset:18432
	ds_read_b128 v[162:165], v110
	ds_read_b128 v[166:169], v110 offset:2048
	ds_read_b128 v[170:173], v112 offset:20480
	ds_read_b128 v[174:177], v113 offset:16384
	s_waitcnt lgkmcnt(3)
	v_mfma_f32_16x16x32_bf16 v[94:97], v[154:157], v[162:165], v[94:97]
	v_mfma_f32_16x16x32_bf16 v[90:93], v[158:161], v[162:165], v[90:93]
	s_waitcnt lgkmcnt(1)
	v_mfma_f32_16x16x32_bf16 v[86:89], v[170:173], v[162:165], v[86:89]
	s_waitcnt lgkmcnt(0)
	v_mfma_f32_16x16x32_bf16 v[82:85], v[174:177], v[162:165], v[82:85]
	v_mfma_f32_16x16x32_bf16 v[78:81], v[154:157], v[166:169], v[78:81]
	v_mfma_f32_16x16x32_bf16 v[62:65], v[158:161], v[166:169], v[62:65]
	v_mfma_f32_16x16x32_bf16 v[46:49], v[170:173], v[166:169], v[46:49]
	v_mfma_f32_16x16x32_bf16 v[26:29], v[174:177], v[166:169], v[26:29]
	ds_read_b128 v[162:165], v110 offset:4096
	ds_read_b128 v[166:169], v111
	s_waitcnt lgkmcnt(1)
	v_mfma_f32_16x16x32_bf16 v[38:41], v[154:157], v[162:165], v[38:41]
	v_mfma_f32_16x16x32_bf16 v[30:33], v[158:161], v[162:165], v[30:33]
	v_mfma_f32_16x16x32_bf16 v[22:25], v[170:173], v[162:165], v[22:25]
	v_mfma_f32_16x16x32_bf16 v[18:21], v[174:177], v[162:165], v[18:21]
	s_waitcnt lgkmcnt(0)
	v_mfma_f32_16x16x32_bf16 v[14:17], v[154:157], v[166:169], v[14:17]
	ds_read_b128 v[154:157], v116 offset:16384
	v_mfma_f32_16x16x32_bf16 v[10:13], v[158:161], v[166:169], v[10:13]
	v_mfma_f32_16x16x32_bf16 v[6:9], v[170:173], v[166:169], v[6:9]
	v_mfma_f32_16x16x32_bf16 v[2:5], v[174:177], v[166:169], v[2:5]
	ds_read_b128 v[158:161], v116 offset:18432
	ds_read_b128 v[162:165], v114
	ds_read_b128 v[166:169], v114 offset:2048
	ds_read_b128 v[170:173], v116 offset:20480
	ds_read_b128 v[174:177], v117 offset:16384
	s_waitcnt lgkmcnt(3)
	v_mfma_f32_16x16x32_bf16 v[94:97], v[154:157], v[162:165], v[94:97]
	v_mfma_f32_16x16x32_bf16 v[90:93], v[158:161], v[162:165], v[90:93]
	s_waitcnt lgkmcnt(1)
	v_mfma_f32_16x16x32_bf16 v[86:89], v[170:173], v[162:165], v[86:89]
	s_waitcnt lgkmcnt(0)
	v_mfma_f32_16x16x32_bf16 v[82:85], v[174:177], v[162:165], v[82:85]
	v_mfma_f32_16x16x32_bf16 v[78:81], v[154:157], v[166:169], v[78:81]
	v_mfma_f32_16x16x32_bf16 v[62:65], v[158:161], v[166:169], v[62:65]
	v_mfma_f32_16x16x32_bf16 v[46:49], v[170:173], v[166:169], v[46:49]
	v_mfma_f32_16x16x32_bf16 v[26:29], v[174:177], v[166:169], v[26:29]
	ds_read_b128 v[162:165], v114 offset:4096
	ds_read_b128 v[166:169], v115
	s_waitcnt lgkmcnt(1)
	v_mfma_f32_16x16x32_bf16 v[38:41], v[154:157], v[162:165], v[38:41]
	v_mfma_f32_16x16x32_bf16 v[30:33], v[158:161], v[162:165], v[30:33]
	v_mfma_f32_16x16x32_bf16 v[22:25], v[170:173], v[162:165], v[22:25]
	v_mfma_f32_16x16x32_bf16 v[18:21], v[174:177], v[162:165], v[18:21]
	s_waitcnt lgkmcnt(0)
	v_mfma_f32_16x16x32_bf16 v[14:17], v[154:157], v[166:169], v[14:17]
	v_mfma_f32_16x16x32_bf16 v[10:13], v[158:161], v[166:169], v[10:13]
	v_mfma_f32_16x16x32_bf16 v[6:9], v[170:173], v[166:169], v[6:9]
	v_mfma_f32_16x16x32_bf16 v[2:5], v[174:177], v[166:169], v[2:5]
	s_setprio 0
	s_waitcnt vmcnt(0)
	s_barrier
	s_add_i32 s0, s5, 0x80
	s_min_u32 s0, s0, 0x3c0
	s_lshl_b32 s0, s0, 1
	s_add_u32 m0, s6, 0x0
	v_lshl_add_u64 v[204:205], v[188:189], 0, s[0:1]
	global_load_lds_dwordx4 v[204:205], off
	s_add_u32 m0, s6, 0x1000
	v_lshl_add_u64 v[206:207], v[190:191], 0, s[0:1]
	global_load_lds_dwordx4 v[206:207], off
	s_add_u32 m0, s6, 0x2000
	v_lshl_add_u64 v[204:205], v[192:193], 0, s[0:1]
	global_load_lds_dwordx4 v[204:205], off
	s_add_u32 m0, s6, 0x3000
	v_lshl_add_u64 v[206:207], v[194:195], 0, s[0:1]
	global_load_lds_dwordx4 v[206:207], off
	s_add_u32 m0, s6, 0x4000
	v_lshl_add_u64 v[204:205], v[196:197], 0, s[0:1]
	global_load_lds_dwordx4 v[204:205], off
	s_add_u32 m0, s6, 0x5000
	v_lshl_add_u64 v[206:207], v[198:199], 0, s[0:1]
	global_load_lds_dwordx4 v[206:207], off
	s_add_u32 m0, s6, 0x6000
	v_lshl_add_u64 v[204:205], v[200:201], 0, s[0:1]
	global_load_lds_dwordx4 v[204:205], off
	s_add_u32 m0, s6, 0x7000
	v_lshl_add_u64 v[206:207], v[202:203], 0, s[0:1]
	global_load_lds_dwordx4 v[206:207], off
	s_setprio 1
	ds_read_b128 v[154:157], v112 offset:49152
	ds_read_b128 v[158:161], v112 offset:51200
	ds_read_b128 v[162:165], v110 offset:32768
	ds_read_b128 v[166:169], v110 offset:34816
	ds_read_b128 v[170:173], v112 offset:53248
	ds_read_b128 v[174:177], v113 offset:49152
	s_waitcnt lgkmcnt(3)
	v_mfma_f32_16x16x32_bf16 v[94:97], v[154:157], v[162:165], v[94:97]
	v_mfma_f32_16x16x32_bf16 v[90:93], v[158:161], v[162:165], v[90:93]
	s_waitcnt lgkmcnt(1)
	v_mfma_f32_16x16x32_bf16 v[86:89], v[170:173], v[162:165], v[86:89]
	s_waitcnt lgkmcnt(0)
	v_mfma_f32_16x16x32_bf16 v[82:85], v[174:177], v[162:165], v[82:85]
	v_mfma_f32_16x16x32_bf16 v[78:81], v[154:157], v[166:169], v[78:81]
	v_mfma_f32_16x16x32_bf16 v[62:65], v[158:161], v[166:169], v[62:65]
	v_mfma_f32_16x16x32_bf16 v[46:49], v[170:173], v[166:169], v[46:49]
	v_mfma_f32_16x16x32_bf16 v[26:29], v[174:177], v[166:169], v[26:29]
	ds_read_b128 v[162:165], v110 offset:36864
	ds_read_b128 v[166:169], v111 offset:32768
	s_waitcnt lgkmcnt(1)
	v_mfma_f32_16x16x32_bf16 v[38:41], v[154:157], v[162:165], v[38:41]
	v_mfma_f32_16x16x32_bf16 v[30:33], v[158:161], v[162:165], v[30:33]
	v_mfma_f32_16x16x32_bf16 v[22:25], v[170:173], v[162:165], v[22:25]
	v_mfma_f32_16x16x32_bf16 v[18:21], v[174:177], v[162:165], v[18:21]
	s_waitcnt lgkmcnt(0)
	v_mfma_f32_16x16x32_bf16 v[14:17], v[154:157], v[166:169], v[14:17]
	ds_read_b128 v[154:157], v116 offset:49152
	v_mfma_f32_16x16x32_bf16 v[10:13], v[158:161], v[166:169], v[10:13]
	v_mfma_f32_16x16x32_bf16 v[6:9], v[170:173], v[166:169], v[6:9]
	v_mfma_f32_16x16x32_bf16 v[2:5], v[174:177], v[166:169], v[2:5]
	ds_read_b128 v[158:161], v116 offset:51200
	ds_read_b128 v[162:165], v114 offset:32768
	ds_read_b128 v[166:169], v114 offset:34816
	ds_read_b128 v[170:173], v116 offset:53248
	ds_read_b128 v[174:177], v117 offset:49152
	s_waitcnt lgkmcnt(3)
	v_mfma_f32_16x16x32_bf16 v[94:97], v[154:157], v[162:165], v[94:97]
	v_mfma_f32_16x16x32_bf16 v[90:93], v[158:161], v[162:165], v[90:93]
	s_waitcnt lgkmcnt(1)
	v_mfma_f32_16x16x32_bf16 v[86:89], v[170:173], v[162:165], v[86:89]
	s_waitcnt lgkmcnt(0)
	v_mfma_f32_16x16x32_bf16 v[82:85], v[174:177], v[162:165], v[82:85]
	v_mfma_f32_16x16x32_bf16 v[78:81], v[154:157], v[166:169], v[78:81]
	v_mfma_f32_16x16x32_bf16 v[62:65], v[158:161], v[166:169], v[62:65]
	v_mfma_f32_16x16x32_bf16 v[46:49], v[170:173], v[166:169], v[46:49]
	v_mfma_f32_16x16x32_bf16 v[26:29], v[174:177], v[166:169], v[26:29]
	ds_read_b128 v[162:165], v114 offset:36864
	ds_read_b128 v[166:169], v115 offset:32768
	s_waitcnt lgkmcnt(1)
	v_mfma_f32_16x16x32_bf16 v[38:41], v[154:157], v[162:165], v[38:41]
	v_mfma_f32_16x16x32_bf16 v[30:33], v[158:161], v[162:165], v[30:33]
	v_mfma_f32_16x16x32_bf16 v[22:25], v[170:173], v[162:165], v[22:25]
	v_mfma_f32_16x16x32_bf16 v[18:21], v[174:177], v[162:165], v[18:21]
	s_waitcnt lgkmcnt(0)
	v_mfma_f32_16x16x32_bf16 v[14:17], v[154:157], v[166:169], v[14:17]
	v_mfma_f32_16x16x32_bf16 v[10:13], v[158:161], v[166:169], v[10:13]
	v_mfma_f32_16x16x32_bf16 v[6:9], v[170:173], v[166:169], v[6:9]
	v_mfma_f32_16x16x32_bf16 v[2:5], v[174:177], v[166:169], v[2:5]
	s_setprio 0
	s_add_i32 s5, s5, 0x80
	s_add_i32 s4, s4, 2
	s_waitcnt vmcnt(0)
	s_barrier
	s_cmp_gt_u32 s4, 13
	s_cbranch_scc0 .Lglds_2829
	v_readlane_b32 s36, v254, 40
	s_waitcnt vmcnt(7)
	v_or_b32_e32 v35, s2, v118
	v_readlane_b32 s48, v254, 52
	v_readlane_b32 s49, v254, 53
	v_or_b32_e32 v34, s3, v119
	s_waitcnt vmcnt(6)
	v_add_u32_e32 v42, v35, v120
	v_mov_b64_e32 v[36:37], s[48:49]
	v_mad_i64_i32 v[36:37], s[2:3], v42, s18, v[36:37]
	v_cmp_gt_i32_e32 vcc, s19, v34
	v_ashrrev_i32_e32 v35, 31, v34
	v_readlane_b32 s37, v254, 41
	v_readlane_b32 s38, v254, 42
	v_readlane_b32 s39, v254, 43
	v_readlane_b32 s40, v254, 44
	v_readlane_b32 s41, v254, 45
	v_readlane_b32 s42, v254, 46
	v_readlane_b32 s43, v254, 47
	v_readlane_b32 s44, v254, 48
	v_readlane_b32 s45, v254, 49
	v_readlane_b32 s46, v254, 50
	v_readlane_b32 s47, v254, 51
	v_readlane_b32 s50, v254, 54
	v_readlane_b32 s51, v254, 55
	s_and_saveexec_b64 s[2:3], vcc
	s_cbranch_execnz .LBB0_205
	s_or_b64 exec, exec, s[2:3]
	v_cmp_gt_i32_e64 s[4:5], s20, v34
	s_and_saveexec_b64 s[2:3], s[4:5]
	s_cbranch_execnz .LBB0_206

.LBB0_220:
	s_ashr_i32 s12, s2, 6
	s_ashr_i32 s13, s12, 31
	s_lshl_b64 s[16:17], s[12:13], 20
	s_add_u32 s18, s36, s16
	s_addc_u32 s19, s37, s17
	s_lshl_b32 s0, s2, 5
	s_and_b32 s16, s0, 0x780
	s_lshl_b32 s0, s2, 7
	s_and_b32 s17, s0, 0x180
	v_or_b32_e32 v2, s16, v1
	v_lshlrev_b32_e32 v98, 11, v2
	v_or_b32_e32 v2, s17, v1
	v_lshl_add_u64 v[104:105], v[100:101], 0, v[98:99]
	v_lshlrev_b32_e32 v98, 11, v2
	v_lshl_add_u64 v[2:3], s[18:19], 0, v[98:99]
	v_lshl_add_u64 v[108:109], v[2:3], 0, v[102:103]
	s_mov_b32 s18, -2
	s_mov_b32 s19, s1
	v_mov_b32_e32 v34, 0
	v_mov_b32_e32 v35, v99
	v_mov_b32_e32 v36, v99
	v_mov_b32_e32 v37, v99
	v_mov_b32_e32 v38, 0
	v_mov_b32_e32 v39, v99
	v_mov_b32_e32 v40, v99
	v_mov_b32_e32 v41, v99
	v_mov_b32_e32 v54, 0
	v_mov_b32_e32 v55, v99
	v_mov_b32_e32 v56, v99
	v_mov_b32_e32 v57, v99
	v_mov_b32_e32 v78, 0
	v_mov_b32_e32 v79, v99
	v_mov_b32_e32 v80, v99
	v_mov_b32_e32 v81, v99
	v_mov_b32_e32 v82, 0
	v_mov_b32_e32 v83, v99
	v_mov_b32_e32 v84, v99
	v_mov_b32_e32 v85, v99
	v_mov_b32_e32 v86, 0
	v_mov_b32_e32 v87, v99
	v_mov_b32_e32 v88, v99
	v_mov_b32_e32 v89, v99
	v_mov_b32_e32 v90, 0
	v_mov_b32_e32 v91, v99
	v_mov_b32_e32 v92, v99
	v_mov_b32_e32 v93, v99
	v_mov_b32_e32 v94, 0
	v_mov_b32_e32 v95, v99
	v_mov_b32_e32 v96, v99
	v_mov_b32_e32 v97, v99
	v_mov_b32_e32 v74, 0
	v_mov_b32_e32 v75, v99
	v_mov_b32_e32 v76, v99
	v_mov_b32_e32 v77, v99
	v_mov_b32_e32 v70, 0
	v_mov_b32_e32 v71, v99
	v_mov_b32_e32 v72, v99
	v_mov_b32_e32 v73, v99
	v_mov_b32_e32 v66, 0
	v_mov_b32_e32 v67, v99
	v_mov_b32_e32 v68, v99
	v_mov_b32_e32 v69, v99
	v_mov_b32_e32 v62, 0
	v_mov_b32_e32 v63, v99
	v_mov_b32_e32 v64, v99
	v_mov_b32_e32 v65, v99
	v_mov_b32_e32 v58, 0
	v_mov_b32_e32 v59, v99
	v_mov_b32_e32 v60, v99
	v_mov_b32_e32 v61, v99
	v_mov_b32_e32 v50, 0
	v_mov_b32_e32 v51, v99
	v_mov_b32_e32 v52, v99
	v_mov_b32_e32 v53, v99
	v_mov_b32_e32 v46, 0
	v_mov_b32_e32 v47, v99
	v_mov_b32_e32 v48, v99
	v_mov_b32_e32 v49, v99
	v_mov_b32_e32 v42, 0
	v_mov_b32_e32 v43, v99
	v_mov_b32_e32 v44, v99
	v_mov_b32_e32 v45, v99
	v_and_b32_e32 v181, 7, v106
	v_bfe_u32 v180, v106, 3, 3
	v_xor_b32_e32 v180, v181, v180
	v_sub_u32_e32 v180, v180, v181
	v_lshlrev_b32_e32 v180, 4, v180
	v_ashrrev_i32_e32 v181, 31, v180
	v_lshrrev_b32_e32 v186, 6, v106
	v_mov_b32_e32 v187, 0x110
	v_lshl_add_u32 v186, v186, 10, v187
	v_lshl_add_u64 v[188:189], v[104:105], 0, v[180:181]
	v_lshl_add_u64 v[196:197], v[108:109], 0, v[180:181]
	v_readfirstlane_b32 s20, v186
	v_add_co_u32_e32 v190, vcc, s3, v188
	v_addc_co_u32_e32 v191, vcc, 0, v189, vcc
	v_add_co_u32_e32 v192, vcc, s14, v188
	v_addc_co_u32_e32 v193, vcc, 0, v189, vcc
	v_add_co_u32_e32 v194, vcc, s15, v188
	v_addc_co_u32_e32 v195, vcc, 0, v189, vcc
	v_add_co_u32_e32 v198, vcc, s3, v196
	v_addc_co_u32_e32 v199, vcc, 0, v197, vcc
	v_add_co_u32_e32 v200, vcc, s14, v196
	v_addc_co_u32_e32 v201, vcc, 0, v197, vcc
	v_add_co_u32_e32 v202, vcc, s15, v196
	v_addc_co_u32_e32 v203, vcc, 0, v197, vcc
	s_add_u32 m0, s20, 0x0
	s_nop 0
	global_load_lds_dwordx4 v[188:189], off
	s_add_u32 m0, s20, 0x1000
	s_nop 0
	global_load_lds_dwordx4 v[190:191], off
	s_add_u32 m0, s20, 0x2000
	s_nop 0
	global_load_lds_dwordx4 v[192:193], off
	s_add_u32 m0, s20, 0x3000
	s_nop 0
	global_load_lds_dwordx4 v[194:195], off
	s_add_u32 m0, s20, 0x4000
	s_nop 0
	global_load_lds_dwordx4 v[196:197], off
	s_add_u32 m0, s20, 0x5000
	s_nop 0
	global_load_lds_dwordx4 v[198:199], off
	s_add_u32 m0, s20, 0x6000
	s_nop 0
	global_load_lds_dwordx4 v[200:201], off
	s_add_u32 m0, s20, 0x7000
	s_nop 0
	global_load_lds_dwordx4 v[202:203], off
	s_mov_b32 s19, 0
	s_mov_b32 s18, -2
	s_waitcnt vmcnt(0)
	s_barrier
.Lglds_3547:
	s_add_i32 s0, s19, 0x40
	s_lshl_b32 s0, s0, 1
	s_add_u32 m0, s20, 0x8000
	v_lshl_add_u64 v[204:205], v[188:189], 0, s[0:1]
	global_load_lds_dwordx4 v[204:205], off
	s_add_u32 m0, s20, 0x9000
	v_lshl_add_u64 v[206:207], v[190:191], 0, s[0:1]
	global_load_lds_dwordx4 v[206:207], off
	s_add_u32 m0, s20, 0xa000
	v_lshl_add_u64 v[204:205], v[192:193], 0, s[0:1]
	global_load_lds_dwordx4 v[204:205], off
	s_add_u32 m0, s20, 0xb000
	v_lshl_add_u64 v[206:207], v[194:195], 0, s[0:1]
	global_load_lds_dwordx4 v[206:207], off
	s_add_u32 m0, s20, 0xc000
	v_lshl_add_u64 v[204:205], v[196:197], 0, s[0:1]
	global_load_lds_dwordx4 v[204:205], off
	s_add_u32 m0, s20, 0xd000
	v_lshl_add_u64 v[206:207], v[198:199], 0, s[0:1]
	global_load_lds_dwordx4 v[206:207], off
	s_add_u32 m0, s20, 0xe000
	v_lshl_add_u64 v[204:205], v[200:201], 0, s[0:1]
	global_load_lds_dwordx4 v[204:205], off
	s_add_u32 m0, s20, 0xf000
	v_lshl_add_u64 v[206:207], v[202:203], 0, s[0:1]
	global_load_lds_dwordx4 v[206:207], off
	s_setprio 1
	ds_read_b128 v[152:155], v112 offset:16384
	ds_read_b128 v[156:159], v112 offset:18432
	ds_read_b128 v[160:163], v110
	ds_read_b128 v[164:167], v110 offset:2048
	ds_read_b128 v[168:171], v112 offset:20480
	ds_read_b128 v[172:175], v113 offset:16384
	s_waitcnt lgkmcnt(3)
	v_mfma_f32_16x16x32_bf16 v[94:97], v[152:155], v[160:163], v[94:97]
	v_mfma_f32_16x16x32_bf16 v[90:93], v[156:159], v[160:163], v[90:93]
	s_waitcnt lgkmcnt(1)
	v_mfma_f32_16x16x32_bf16 v[86:89], v[168:171], v[160:163], v[86:89]
	s_waitcnt lgkmcnt(0)
	v_mfma_f32_16x16x32_bf16 v[82:85], v[172:175], v[160:163], v[82:85]
	v_mfma_f32_16x16x32_bf16 v[78:81], v[152:155], v[164:167], v[78:81]
	v_mfma_f32_16x16x32_bf16 v[54:57], v[156:159], v[164:167], v[54:57]
	v_mfma_f32_16x16x32_bf16 v[38:41], v[168:171], v[164:167], v[38:41]
	v_mfma_f32_16x16x32_bf16 v[34:37], v[172:175], v[164:167], v[34:37]
	ds_read_b128 v[160:163], v110 offset:4096
	ds_read_b128 v[164:167], v111
	s_waitcnt lgkmcnt(1)
	v_mfma_f32_16x16x32_bf16 v[74:77], v[152:155], v[160:163], v[74:77]
	v_mfma_f32_16x16x32_bf16 v[70:73], v[156:159], v[160:163], v[70:73]
	v_mfma_f32_16x16x32_bf16 v[66:69], v[168:171], v[160:163], v[66:69]
	v_mfma_f32_16x16x32_bf16 v[62:65], v[172:175], v[160:163], v[62:65]
	s_waitcnt lgkmcnt(0)
	v_mfma_f32_16x16x32_bf16 v[58:61], v[152:155], v[164:167], v[58:61]
	ds_read_b128 v[152:155], v116 offset:16384
	v_mfma_f32_16x16x32_bf16 v[50:53], v[156:159], v[164:167], v[50:53]
	v_mfma_f32_16x16x32_bf16 v[46:49], v[168:171], v[164:167], v[46:49]
	v_mfma_f32_16x16x32_bf16 v[42:45], v[172:175], v[164:167], v[42:45]
	ds_read_b128 v[156:159], v116 offset:18432
	ds_read_b128 v[160:163], v114
	ds_read_b128 v[164:167], v114 offset:2048
	ds_read_b128 v[168:171], v116 offset:20480
	ds_read_b128 v[172:175], v117 offset:16384
	s_waitcnt lgkmcnt(3)
	v_mfma_f32_16x16x32_bf16 v[94:97], v[152:155], v[160:163], v[94:97]
	v_mfma_f32_16x16x32_bf16 v[90:93], v[156:159], v[160:163], v[90:93]
	s_waitcnt lgkmcnt(1)
	v_mfma_f32_16x16x32_bf16 v[86:89], v[168:171], v[160:163], v[86:89]
	s_waitcnt lgkmcnt(0)
	v_mfma_f32_16x16x32_bf16 v[82:85], v[172:175], v[160:163], v[82:85]
	v_mfma_f32_16x16x32_bf16 v[78:81], v[152:155], v[164:167], v[78:81]
	v_mfma_f32_16x16x32_bf16 v[54:57], v[156:159], v[164:167], v[54:57]
	v_mfma_f32_16x16x32_bf16 v[38:41], v[168:171], v[164:167], v[38:41]
	v_mfma_f32_16x16x32_bf16 v[34:37], v[172:175], v[164:167], v[34:37]
	ds_read_b128 v[160:163], v114 offset:4096
	ds_read_b128 v[164:167], v115
	s_waitcnt lgkmcnt(1)
	v_mfma_f32_16x16x32_bf16 v[74:77], v[152:155], v[160:163], v[74:77]
	v_mfma_f32_16x16x32_bf16 v[70:73], v[156:159], v[160:163], v[70:73]
	v_mfma_f32_16x16x32_bf16 v[66:69], v[168:171], v[160:163], v[66:69]
	v_mfma_f32_16x16x32_bf16 v[62:65], v[172:175], v[160:163], v[62:65]
	s_waitcnt lgkmcnt(0)
	v_mfma_f32_16x16x32_bf16 v[58:61], v[152:155], v[164:167], v[58:61]
	v_mfma_f32_16x16x32_bf16 v[50:53], v[156:159], v[164:167], v[50:53]
	v_mfma_f32_16x16x32_bf16 v[46:49], v[168:171], v[164:167], v[46:49]
	v_mfma_f32_16x16x32_bf16 v[42:45], v[172:175], v[164:167], v[42:45]
	s_setprio 0
	s_waitcnt vmcnt(0)
	s_barrier
	s_add_i32 s0, s19, 0x80
	s_min_u32 s0, s0, 0x3c0
	s_lshl_b32 s0, s0, 1
	s_add_u32 m0, s20, 0x0
	v_lshl_add_u64 v[204:205], v[188:189], 0, s[0:1]
	global_load_lds_dwordx4 v[204:205], off
	s_add_u32 m0, s20, 0x1000
	v_lshl_add_u64 v[206:207], v[190:191], 0, s[0:1]
	global_load_lds_dwordx4 v[206:207], off
	s_add_u32 m0, s20, 0x2000
	v_lshl_add_u64 v[204:205], v[192:193], 0, s[0:1]
	global_load_lds_dwordx4 v[204:205], off
	s_add_u32 m0, s20, 0x3000
	v_lshl_add_u64 v[206:207], v[194:195], 0, s[0:1]
	global_load_lds_dwordx4 v[206:207], off
	s_add_u32 m0, s20, 0x4000
	v_lshl_add_u64 v[204:205], v[196:197], 0, s[0:1]
	global_load_lds_dwordx4 v[204:205], off
	s_add_u32 m0, s20, 0x5000
	v_lshl_add_u64 v[206:207], v[198:199], 0, s[0:1]
	global_load_lds_dwordx4 v[206:207], off
	s_add_u32 m0, s20, 0x6000
	v_lshl_add_u64 v[204:205], v[200:201], 0, s[0:1]
	global_load_lds_dwordx4 v[204:205], off
	s_add_u32 m0, s20, 0x7000
	v_lshl_add_u64 v[206:207], v[202:203], 0, s[0:1]
	global_load_lds_dwordx4 v[206:207], off
	s_setprio 1
	ds_read_b128 v[152:155], v112 offset:49152
	ds_read_b128 v[156:159], v112 offset:51200
	ds_read_b128 v[160:163], v110 offset:32768
	ds_read_b128 v[164:167], v110 offset:34816
	ds_read_b128 v[168:171], v112 offset:53248
	ds_read_b128 v[172:175], v113 offset:49152
	s_waitcnt lgkmcnt(3)
	v_mfma_f32_16x16x32_bf16 v[94:97], v[152:155], v[160:163], v[94:97]
	v_mfma_f32_16x16x32_bf16 v[90:93], v[156:159], v[160:163], v[90:93]
	s_waitcnt lgkmcnt(1)
	v_mfma_f32_16x16x32_bf16 v[86:89], v[168:171], v[160:163], v[86:89]
	s_waitcnt lgkmcnt(0)
	v_mfma_f32_16x16x32_bf16 v[82:85], v[172:175], v[160:163], v[82:85]
	v_mfma_f32_16x16x32_bf16 v[78:81], v[152:155], v[164:167], v[78:81]
	v_mfma_f32_16x16x32_bf16 v[54:57], v[156:159], v[164:167], v[54:57]
	v_mfma_f32_16x16x32_bf16 v[38:41], v[168:171], v[164:167], v[38:41]
	v_mfma_f32_16x16x32_bf16 v[34:37], v[172:175], v[164:167], v[34:37]
	ds_read_b128 v[160:163], v110 offset:36864
	ds_read_b128 v[164:167], v111 offset:32768
	s_waitcnt lgkmcnt(1)
	v_mfma_f32_16x16x32_bf16 v[74:77], v[152:155], v[160:163], v[74:77]
	v_mfma_f32_16x16x32_bf16 v[70:73], v[156:159], v[160:163], v[70:73]
	v_mfma_f32_16x16x32_bf16 v[66:69], v[168:171], v[160:163], v[66:69]
	v_mfma_f32_16x16x32_bf16 v[62:65], v[172:175], v[160:163], v[62:65]
	s_waitcnt lgkmcnt(0)
	v_mfma_f32_16x16x32_bf16 v[58:61], v[152:155], v[164:167], v[58:61]
	ds_read_b128 v[152:155], v116 offset:49152
	v_mfma_f32_16x16x32_bf16 v[50:53], v[156:159], v[164:167], v[50:53]
	v_mfma_f32_16x16x32_bf16 v[46:49], v[168:171], v[164:167], v[46:49]
	v_mfma_f32_16x16x32_bf16 v[42:45], v[172:175], v[164:167], v[42:45]
	ds_read_b128 v[156:159], v116 offset:51200
	ds_read_b128 v[160:163], v114 offset:32768
	ds_read_b128 v[164:167], v114 offset:34816
	ds_read_b128 v[168:171], v116 offset:53248
	ds_read_b128 v[172:175], v117 offset:49152
	s_waitcnt lgkmcnt(3)
	v_mfma_f32_16x16x32_bf16 v[94:97], v[152:155], v[160:163], v[94:97]
	v_mfma_f32_16x16x32_bf16 v[90:93], v[156:159], v[160:163], v[90:93]
	s_waitcnt lgkmcnt(1)
	v_mfma_f32_16x16x32_bf16 v[86:89], v[168:171], v[160:163], v[86:89]
	s_waitcnt lgkmcnt(0)
	v_mfma_f32_16x16x32_bf16 v[82:85], v[172:175], v[160:163], v[82:85]
	v_mfma_f32_16x16x32_bf16 v[78:81], v[152:155], v[164:167], v[78:81]
	v_mfma_f32_16x16x32_bf16 v[54:57], v[156:159], v[164:167], v[54:57]
	v_mfma_f32_16x16x32_bf16 v[38:41], v[168:171], v[164:167], v[38:41]
	v_mfma_f32_16x16x32_bf16 v[34:37], v[172:175], v[164:167], v[34:37]
	ds_read_b128 v[160:163], v114 offset:36864
	ds_read_b128 v[164:167], v115 offset:32768
	s_waitcnt lgkmcnt(1)
	v_mfma_f32_16x16x32_bf16 v[74:77], v[152:155], v[160:163], v[74:77]
	v_mfma_f32_16x16x32_bf16 v[70:73], v[156:159], v[160:163], v[70:73]
	v_mfma_f32_16x16x32_bf16 v[66:69], v[168:171], v[160:163], v[66:69]
	v_mfma_f32_16x16x32_bf16 v[62:65], v[172:175], v[160:163], v[62:65]
	s_waitcnt lgkmcnt(0)
	v_mfma_f32_16x16x32_bf16 v[58:61], v[152:155], v[164:167], v[58:61]
	v_mfma_f32_16x16x32_bf16 v[50:53], v[156:159], v[164:167], v[50:53]
	v_mfma_f32_16x16x32_bf16 v[46:49], v[168:171], v[164:167], v[46:49]
	v_mfma_f32_16x16x32_bf16 v[42:45], v[172:175], v[164:167], v[42:45]
	s_setprio 0
	s_add_i32 s19, s19, 0x80
	s_add_i32 s18, s18, 2
	s_waitcnt vmcnt(0)
	s_barrier
	s_cmp_lt_u32 s18, 14
	s_cbranch_scc1 .Lglds_3547
	v_readlane_b32 s36, v254, 40
	s_lshl_b64 s[12:13], s[12:13], 21
	v_readlane_b32 s50, v254, 54
	v_readlane_b32 s51, v254, 55
	s_add_u32 s12, s50, s12
	s_addc_u32 s13, s51, s13
	s_waitcnt vmcnt(7)
	v_or_b32_e32 v4, s17, v119
	v_add_lshl_u32 v98, v118, s16, 10
	v_lshl_add_u64 v[2:3], s[12:13], 0, v[98:99]
	v_lshlrev_b32_e32 v98, 1, v4
	v_lshl_add_u64 v[4:5], v[2:3], 0, v[98:99]
	s_waitcnt vmcnt(6)
	v_cvt_pk_bf16_f32 v6, v94, v95
	v_cvt_pk_bf16_f32 v7, v96, v97
	global_store_dwordx2 v[4:5], v[6:7], off
	v_cvt_pk_bf16_f32 v6, v90, v91
	v_cvt_pk_bf16_f32 v7, v92, v93
	global_store_dwordx2 v[4:5], v[6:7], off offset:32
	v_cvt_pk_bf16_f32 v6, v86, v87
	v_cvt_pk_bf16_f32 v7, v88, v89
	global_store_dwordx2 v[4:5], v[6:7], off offset:64
	v_cvt_pk_bf16_f32 v6, v82, v83
	v_cvt_pk_bf16_f32 v7, v84, v85
	global_store_dwordx2 v[4:5], v[6:7], off offset:96
	v_lshl_add_u64 v[4:5], v[2:3], 0, s[4:5]
	v_lshl_add_u64 v[6:7], v[4:5], 0, v[98:99]
	v_cvt_pk_bf16_f32 v8, v78, v79
	v_cvt_pk_bf16_f32 v9, v80, v81
	global_store_dwordx2 v[6:7], v[8:9], off
	v_or_b32_e32 v6, 32, v98
	v_mov_b32_e32 v7, v99
	v_lshl_add_u64 v[8:9], v[4:5], 0, v[6:7]
	s_waitcnt vmcnt(10)
	v_cvt_pk_bf16_f32 v10, v54, v55
	v_cvt_pk_bf16_f32 v11, v56, v57
	global_store_dwordx2 v[8:9], v[10:11], off
	v_or_b32_e32 v8, 64, v98
	v_mov_b32_e32 v9, v99
	v_lshl_add_u64 v[10:11], v[4:5], 0, v[8:9]
	v_cvt_pk_bf16_f32 v12, v38, v39
	v_cvt_pk_bf16_f32 v13, v40, v41
	global_store_dwordx2 v[10:11], v[12:13], off
	v_or_b32_e32 v10, 0x60, v98
	v_mov_b32_e32 v11, v99
	v_lshl_add_u64 v[4:5], v[4:5], 0, v[10:11]
	v_cvt_pk_bf16_f32 v12, v34, v35
	v_cvt_pk_bf16_f32 v13, v36, v37
	global_store_dwordx2 v[4:5], v[12:13], off
	v_lshl_add_u64 v[4:5], v[2:3], 0, s[6:7]
	v_lshl_add_u64 v[12:13], v[4:5], 0, v[98:99]
	s_waitcnt vmcnt(11)
	v_cvt_pk_bf16_f32 v14, v74, v75
	v_cvt_pk_bf16_f32 v15, v76, v77
	global_store_dwordx2 v[12:13], v[14:15], off
	v_lshl_add_u64 v[12:13], v[4:5], 0, v[6:7]
	v_cvt_pk_bf16_f32 v14, v70, v71
	v_cvt_pk_bf16_f32 v15, v72, v73
	global_store_dwordx2 v[12:13], v[14:15], off
	v_lshl_add_u64 v[12:13], v[4:5], 0, v[8:9]
	v_cvt_pk_bf16_f32 v14, v66, v67
	v_cvt_pk_bf16_f32 v15, v68, v69
	global_store_dwordx2 v[12:13], v[14:15], off
	v_lshl_add_u64 v[4:5], v[4:5], 0, v[10:11]
	v_cvt_pk_bf16_f32 v12, v62, v63
	v_cvt_pk_bf16_f32 v13, v64, v65
	v_lshl_add_u64 v[2:3], v[2:3], 0, s[8:9]
	global_store_dwordx2 v[4:5], v[12:13], off
	v_lshl_add_u64 v[4:5], v[2:3], 0, v[98:99]
	v_cvt_pk_bf16_f32 v12, v58, v59
	v_cvt_pk_bf16_f32 v13, v60, v61
	global_store_dwordx2 v[4:5], v[12:13], off
	v_lshl_add_u64 v[4:5], v[2:3], 0, v[6:7]
	v_cvt_pk_bf16_f32 v6, v50, v51
	v_cvt_pk_bf16_f32 v7, v52, v53
	v_readlane_b32 s12, v254, 0
	global_store_dwordx2 v[4:5], v[6:7], off
	v_lshl_add_u64 v[4:5], v[2:3], 0, v[8:9]
	v_cvt_pk_bf16_f32 v6, v46, v47
	v_cvt_pk_bf16_f32 v7, v48, v49
	s_add_i32 s2, s2, s12
	v_readlane_b32 s37, v254, 41
	global_store_dwordx2 v[4:5], v[6:7], off
	v_lshl_add_u64 v[2:3], v[2:3], 0, v[10:11]
	v_cvt_pk_bf16_f32 v4, v42, v43
	v_cvt_pk_bf16_f32 v5, v44, v45
	s_cmpk_lt_i32 s2, 0x80
	v_readlane_b32 s38, v254, 42
	v_readlane_b32 s39, v254, 43
	v_readlane_b32 s40, v254, 44
	v_readlane_b32 s41, v254, 45
	v_readlane_b32 s42, v254, 46
	v_readlane_b32 s43, v254, 47
	v_readlane_b32 s44, v254, 48
	v_readlane_b32 s45, v254, 49
	v_readlane_b32 s46, v254, 50
	v_readlane_b32 s47, v254, 51
	v_readlane_b32 s48, v254, 52
	v_readlane_b32 s49, v254, 53
	v_readlane_b32 s13, v254, 1
	global_store_dwordx2 v[2:3], v[4:5], off
	s_cbranch_scc1 .LBB0_220

.LBB0_422:
	s_and_b32 s4, s7, 0xf8
	s_or_b32 s4, s4, s2
	s_lshl_b32 s11, s4, 7
	s_lshl_b32 s4, s7, 7
	v_or_b32_e32 v2, s11, v1
	s_and_b32 s12, s4, 0x380
	v_lshlrev_b32_e32 v98, 11, v2
	v_lshl_add_u64 v[104:105], v[102:103], 0, v[98:99]
	v_or_b32_e32 v2, s12, v1
	v_lshlrev_b32_e32 v98, 11, v2
	v_lshl_add_u64 v[108:109], v[100:101], 0, v[98:99]
	v_and_b32_e32 v177, 7, v106
	v_bfe_u32 v176, v106, 3, 3
	v_xor_b32_e32 v176, v177, v176
	v_sub_u32_e32 v176, v176, v177
	v_lshlrev_b32_e32 v176, 4, v176
	v_ashrrev_i32_e32 v177, 31, v176
	v_lshrrev_b32_e32 v182, 6, v106
	v_mov_b32_e32 v183, 0x110
	v_lshl_add_u32 v182, v182, 10, v183
	v_lshl_add_u64 v[184:185], v[104:105], 0, v[176:177]
	v_lshl_add_u64 v[192:193], v[108:109], 0, v[176:177]
	v_readfirstlane_b32 s15, v182
	v_add_co_u32_e32 v186, vcc, s8, v184
	v_addc_co_u32_e32 v187, vcc, 0, v185, vcc
	v_add_co_u32_e32 v188, vcc, s9, v184
	v_addc_co_u32_e32 v189, vcc, 0, v185, vcc
	v_add_co_u32_e32 v190, vcc, s10, v184
	v_addc_co_u32_e32 v191, vcc, 0, v185, vcc
	v_add_co_u32_e32 v194, vcc, s8, v192
	v_addc_co_u32_e32 v195, vcc, 0, v193, vcc
	v_add_co_u32_e32 v196, vcc, s9, v192
	v_addc_co_u32_e32 v197, vcc, 0, v193, vcc
	v_add_co_u32_e32 v198, vcc, s10, v192
	v_addc_co_u32_e32 v199, vcc, 0, v193, vcc
	v_mov_b32_e32 v30, 0
	v_mov_b32_e32 v31, v99
	v_mov_b32_e32 v32, v99
	v_mov_b32_e32 v33, v99
	v_mov_b32_e32 v62, 0
	v_mov_b32_e32 v63, v99
	v_mov_b32_e32 v64, v99
	v_mov_b32_e32 v65, v99
	v_mov_b32_e32 v74, 0
	v_mov_b32_e32 v75, v99
	v_mov_b32_e32 v76, v99
	v_mov_b32_e32 v77, v99
	v_mov_b32_e32 v78, 0
	v_mov_b32_e32 v79, v99
	v_mov_b32_e32 v80, v99
	v_mov_b32_e32 v81, v99
	v_mov_b32_e32 v82, 0
	v_mov_b32_e32 v83, v99
	v_mov_b32_e32 v84, v99
	v_mov_b32_e32 v85, v99
	v_mov_b32_e32 v86, 0
	v_mov_b32_e32 v87, v99
	v_mov_b32_e32 v88, v99
	v_mov_b32_e32 v89, v99
	v_mov_b32_e32 v90, 0
	v_mov_b32_e32 v91, v99
	v_mov_b32_e32 v92, v99
	v_mov_b32_e32 v93, v99
	v_mov_b32_e32 v94, 0
	v_mov_b32_e32 v95, v99
	v_mov_b32_e32 v96, v99
	v_mov_b32_e32 v97, v99
	v_mov_b32_e32 v66, 0
	v_mov_b32_e32 v67, v99
	v_mov_b32_e32 v68, v99
	v_mov_b32_e32 v69, v99
	v_mov_b32_e32 v38, 0
	v_mov_b32_e32 v39, v99
	v_mov_b32_e32 v40, v99
	v_mov_b32_e32 v41, v99
	v_mov_b32_e32 v34, 0
	v_mov_b32_e32 v35, v99
	v_mov_b32_e32 v36, v99
	v_mov_b32_e32 v37, v99
	v_mov_b32_e32 v18, 0
	v_mov_b32_e32 v19, v99
	v_mov_b32_e32 v20, v99
	v_mov_b32_e32 v21, v99
	v_mov_b32_e32 v14, 0
	v_mov_b32_e32 v15, v99
	v_mov_b32_e32 v16, v99
	v_mov_b32_e32 v17, v99
	v_mov_b32_e32 v10, 0
	v_mov_b32_e32 v11, v99
	v_mov_b32_e32 v12, v99
	v_mov_b32_e32 v13, v99
	v_mov_b32_e32 v6, 0
	v_mov_b32_e32 v7, v99
	v_mov_b32_e32 v8, v99
	v_mov_b32_e32 v9, v99
	v_mov_b32_e32 v2, 0
	v_mov_b32_e32 v3, v99
	v_mov_b32_e32 v4, v99
	v_mov_b32_e32 v5, v99
	s_add_u32 m0, s15, 0x0
	s_nop 0
	global_load_lds_dwordx4 v[184:185], off
	s_add_u32 m0, s15, 0x1000
	s_nop 0
	global_load_lds_dwordx4 v[186:187], off
	s_add_u32 m0, s15, 0x2000
	s_nop 0
	global_load_lds_dwordx4 v[188:189], off
	s_add_u32 m0, s15, 0x3000
	s_nop 0
	global_load_lds_dwordx4 v[190:191], off
	s_add_u32 m0, s15, 0x4000
	s_nop 0
	global_load_lds_dwordx4 v[192:193], off
	s_add_u32 m0, s15, 0x5000
	s_nop 0
	global_load_lds_dwordx4 v[194:195], off
	s_add_u32 m0, s15, 0x6000
	s_nop 0
	global_load_lds_dwordx4 v[196:197], off
	s_add_u32 m0, s15, 0x7000
	s_nop 0
	global_load_lds_dwordx4 v[198:199], off
	s_mov_b32 s14, 0
	s_mov_b32 s13, -2
	s_waitcnt vmcnt(0)
	s_barrier
.Lglds_12468:
	s_add_i32 s4, s14, 0x40
	s_lshl_b32 s4, s4, 1
	s_add_u32 m0, s15, 0x8000
	v_lshl_add_u64 v[200:201], v[184:185], 0, s[4:5]
	global_load_lds_dwordx4 v[200:201], off
	s_add_u32 m0, s15, 0x9000
	v_lshl_add_u64 v[202:203], v[186:187], 0, s[4:5]
	global_load_lds_dwordx4 v[202:203], off
	s_add_u32 m0, s15, 0xa000
	v_lshl_add_u64 v[200:201], v[188:189], 0, s[4:5]
	global_load_lds_dwordx4 v[200:201], off
	s_add_u32 m0, s15, 0xb000
	v_lshl_add_u64 v[202:203], v[190:191], 0, s[4:5]
	global_load_lds_dwordx4 v[202:203], off
	s_add_u32 m0, s15, 0xc000
	v_lshl_add_u64 v[200:201], v[192:193], 0, s[4:5]
	global_load_lds_dwordx4 v[200:201], off
	s_add_u32 m0, s15, 0xd000
	v_lshl_add_u64 v[202:203], v[194:195], 0, s[4:5]
	global_load_lds_dwordx4 v[202:203], off
	s_add_u32 m0, s15, 0xe000
	v_lshl_add_u64 v[200:201], v[196:197], 0, s[4:5]
	global_load_lds_dwordx4 v[200:201], off
	s_add_u32 m0, s15, 0xf000
	v_lshl_add_u64 v[202:203], v[198:199], 0, s[4:5]
	global_load_lds_dwordx4 v[202:203], off
	s_setprio 1
	ds_read_b128 v[152:155], v112 offset:16384
	ds_read_b128 v[156:159], v112 offset:18432
	ds_read_b128 v[160:163], v110
	ds_read_b128 v[164:167], v110 offset:2048
	ds_read_b128 v[168:171], v112 offset:20480
	ds_read_b128 v[172:175], v113 offset:16384
	s_waitcnt lgkmcnt(3)
	v_mfma_f32_16x16x32_bf16 v[94:97], v[152:155], v[160:163], v[94:97]
	v_mfma_f32_16x16x32_bf16 v[90:93], v[156:159], v[160:163], v[90:93]
	s_waitcnt lgkmcnt(1)
	v_mfma_f32_16x16x32_bf16 v[86:89], v[168:171], v[160:163], v[86:89]
	s_waitcnt lgkmcnt(0)
	v_mfma_f32_16x16x32_bf16 v[82:85], v[172:175], v[160:163], v[82:85]
	v_mfma_f32_16x16x32_bf16 v[78:81], v[152:155], v[164:167], v[78:81]
	v_mfma_f32_16x16x32_bf16 v[74:77], v[156:159], v[164:167], v[74:77]
	v_mfma_f32_16x16x32_bf16 v[62:65], v[168:171], v[164:167], v[62:65]
	v_mfma_f32_16x16x32_bf16 v[30:33], v[172:175], v[164:167], v[30:33]
	ds_read_b128 v[160:163], v110 offset:4096
	ds_read_b128 v[164:167], v111
	s_waitcnt lgkmcnt(1)
	v_mfma_f32_16x16x32_bf16 v[66:69], v[152:155], v[160:163], v[66:69]
	v_mfma_f32_16x16x32_bf16 v[38:41], v[156:159], v[160:163], v[38:41]
	v_mfma_f32_16x16x32_bf16 v[34:37], v[168:171], v[160:163], v[34:37]
	v_mfma_f32_16x16x32_bf16 v[18:21], v[172:175], v[160:163], v[18:21]
	s_waitcnt lgkmcnt(0)
	v_mfma_f32_16x16x32_bf16 v[14:17], v[152:155], v[164:167], v[14:17]
	ds_read_b128 v[152:155], v116 offset:16384
	v_mfma_f32_16x16x32_bf16 v[10:13], v[156:159], v[164:167], v[10:13]
	v_mfma_f32_16x16x32_bf16 v[6:9], v[168:171], v[164:167], v[6:9]
	v_mfma_f32_16x16x32_bf16 v[2:5], v[172:175], v[164:167], v[2:5]
	ds_read_b128 v[156:159], v116 offset:18432
	ds_read_b128 v[160:163], v114
	ds_read_b128 v[164:167], v114 offset:2048
	ds_read_b128 v[168:171], v116 offset:20480
	ds_read_b128 v[172:175], v117 offset:16384
	s_waitcnt lgkmcnt(3)
	v_mfma_f32_16x16x32_bf16 v[94:97], v[152:155], v[160:163], v[94:97]
	v_mfma_f32_16x16x32_bf16 v[90:93], v[156:159], v[160:163], v[90:93]
	s_waitcnt lgkmcnt(1)
	v_mfma_f32_16x16x32_bf16 v[86:89], v[168:171], v[160:163], v[86:89]
	s_waitcnt lgkmcnt(0)
	v_mfma_f32_16x16x32_bf16 v[82:85], v[172:175], v[160:163], v[82:85]
	v_mfma_f32_16x16x32_bf16 v[78:81], v[152:155], v[164:167], v[78:81]
	v_mfma_f32_16x16x32_bf16 v[74:77], v[156:159], v[164:167], v[74:77]
	v_mfma_f32_16x16x32_bf16 v[62:65], v[168:171], v[164:167], v[62:65]
	v_mfma_f32_16x16x32_bf16 v[30:33], v[172:175], v[164:167], v[30:33]
	ds_read_b128 v[160:163], v114 offset:4096
	ds_read_b128 v[164:167], v115
	s_waitcnt lgkmcnt(1)
	v_mfma_f32_16x16x32_bf16 v[66:69], v[152:155], v[160:163], v[66:69]
	v_mfma_f32_16x16x32_bf16 v[38:41], v[156:159], v[160:163], v[38:41]
	v_mfma_f32_16x16x32_bf16 v[34:37], v[168:171], v[160:163], v[34:37]
	v_mfma_f32_16x16x32_bf16 v[18:21], v[172:175], v[160:163], v[18:21]
	s_waitcnt lgkmcnt(0)
	v_mfma_f32_16x16x32_bf16 v[14:17], v[152:155], v[164:167], v[14:17]
	v_mfma_f32_16x16x32_bf16 v[10:13], v[156:159], v[164:167], v[10:13]
	v_mfma_f32_16x16x32_bf16 v[6:9], v[168:171], v[164:167], v[6:9]
	v_mfma_f32_16x16x32_bf16 v[2:5], v[172:175], v[164:167], v[2:5]
	s_setprio 0
	s_waitcnt vmcnt(0)
	s_barrier
	s_add_i32 s4, s14, 0x80
	s_min_u32 s4, s4, 0x3c0
	s_lshl_b32 s4, s4, 1
	s_add_u32 m0, s15, 0x0
	v_lshl_add_u64 v[200:201], v[184:185], 0, s[4:5]
	global_load_lds_dwordx4 v[200:201], off
	s_add_u32 m0, s15, 0x1000
	v_lshl_add_u64 v[202:203], v[186:187], 0, s[4:5]
	global_load_lds_dwordx4 v[202:203], off
	s_add_u32 m0, s15, 0x2000
	v_lshl_add_u64 v[200:201], v[188:189], 0, s[4:5]
	global_load_lds_dwordx4 v[200:201], off
	s_add_u32 m0, s15, 0x3000
	v_lshl_add_u64 v[202:203], v[190:191], 0, s[4:5]
	global_load_lds_dwordx4 v[202:203], off
	s_add_u32 m0, s15, 0x4000
	v_lshl_add_u64 v[200:201], v[192:193], 0, s[4:5]
	global_load_lds_dwordx4 v[200:201], off
	s_add_u32 m0, s15, 0x5000
	v_lshl_add_u64 v[202:203], v[194:195], 0, s[4:5]
	global_load_lds_dwordx4 v[202:203], off
	s_add_u32 m0, s15, 0x6000
	v_lshl_add_u64 v[200:201], v[196:197], 0, s[4:5]
	global_load_lds_dwordx4 v[200:201], off
	s_add_u32 m0, s15, 0x7000
	v_lshl_add_u64 v[202:203], v[198:199], 0, s[4:5]
	global_load_lds_dwordx4 v[202:203], off
	s_setprio 1
	ds_read_b128 v[152:155], v112 offset:49152
	ds_read_b128 v[156:159], v112 offset:51200
	ds_read_b128 v[160:163], v110 offset:32768
	ds_read_b128 v[164:167], v110 offset:34816
	ds_read_b128 v[168:171], v112 offset:53248
	ds_read_b128 v[172:175], v113 offset:49152
	s_waitcnt lgkmcnt(3)
	v_mfma_f32_16x16x32_bf16 v[94:97], v[152:155], v[160:163], v[94:97]
	v_mfma_f32_16x16x32_bf16 v[90:93], v[156:159], v[160:163], v[90:93]
	s_waitcnt lgkmcnt(1)
	v_mfma_f32_16x16x32_bf16 v[86:89], v[168:171], v[160:163], v[86:89]
	s_waitcnt lgkmcnt(0)
	v_mfma_f32_16x16x32_bf16 v[82:85], v[172:175], v[160:163], v[82:85]
	v_mfma_f32_16x16x32_bf16 v[78:81], v[152:155], v[164:167], v[78:81]
	v_mfma_f32_16x16x32_bf16 v[74:77], v[156:159], v[164:167], v[74:77]
	v_mfma_f32_16x16x32_bf16 v[62:65], v[168:171], v[164:167], v[62:65]
	v_mfma_f32_16x16x32_bf16 v[30:33], v[172:175], v[164:167], v[30:33]
	ds_read_b128 v[160:163], v110 offset:36864
	ds_read_b128 v[164:167], v111 offset:32768
	s_waitcnt lgkmcnt(1)
	v_mfma_f32_16x16x32_bf16 v[66:69], v[152:155], v[160:163], v[66:69]
	v_mfma_f32_16x16x32_bf16 v[38:41], v[156:159], v[160:163], v[38:41]
	v_mfma_f32_16x16x32_bf16 v[34:37], v[168:171], v[160:163], v[34:37]
	v_mfma_f32_16x16x32_bf16 v[18:21], v[172:175], v[160:163], v[18:21]
	s_waitcnt lgkmcnt(0)
	v_mfma_f32_16x16x32_bf16 v[14:17], v[152:155], v[164:167], v[14:17]
	ds_read_b128 v[152:155], v116 offset:49152
	v_mfma_f32_16x16x32_bf16 v[10:13], v[156:159], v[164:167], v[10:13]
	v_mfma_f32_16x16x32_bf16 v[6:9], v[168:171], v[164:167], v[6:9]
	v_mfma_f32_16x16x32_bf16 v[2:5], v[172:175], v[164:167], v[2:5]
	ds_read_b128 v[156:159], v116 offset:51200
	ds_read_b128 v[160:163], v114 offset:32768
	ds_read_b128 v[164:167], v114 offset:34816
	ds_read_b128 v[168:171], v116 offset:53248
	ds_read_b128 v[172:175], v117 offset:49152
	s_waitcnt lgkmcnt(3)
	v_mfma_f32_16x16x32_bf16 v[94:97], v[152:155], v[160:163], v[94:97]
	v_mfma_f32_16x16x32_bf16 v[90:93], v[156:159], v[160:163], v[90:93]
	s_waitcnt lgkmcnt(1)
	v_mfma_f32_16x16x32_bf16 v[86:89], v[168:171], v[160:163], v[86:89]
	s_waitcnt lgkmcnt(0)
	v_mfma_f32_16x16x32_bf16 v[82:85], v[172:175], v[160:163], v[82:85]
	v_mfma_f32_16x16x32_bf16 v[78:81], v[152:155], v[164:167], v[78:81]
	v_mfma_f32_16x16x32_bf16 v[74:77], v[156:159], v[164:167], v[74:77]
	v_mfma_f32_16x16x32_bf16 v[62:65], v[168:171], v[164:167], v[62:65]
	v_mfma_f32_16x16x32_bf16 v[30:33], v[172:175], v[164:167], v[30:33]
	ds_read_b128 v[160:163], v114 offset:36864
	ds_read_b128 v[164:167], v115 offset:32768
	s_waitcnt lgkmcnt(1)
	v_mfma_f32_16x16x32_bf16 v[66:69], v[152:155], v[160:163], v[66:69]
	v_mfma_f32_16x16x32_bf16 v[38:41], v[156:159], v[160:163], v[38:41]
	v_mfma_f32_16x16x32_bf16 v[34:37], v[168:171], v[160:163], v[34:37]
	v_mfma_f32_16x16x32_bf16 v[18:21], v[172:175], v[160:163], v[18:21]
	s_waitcnt lgkmcnt(0)
	v_mfma_f32_16x16x32_bf16 v[14:17], v[152:155], v[164:167], v[14:17]
	v_mfma_f32_16x16x32_bf16 v[10:13], v[156:159], v[164:167], v[10:13]
	v_mfma_f32_16x16x32_bf16 v[6:9], v[168:171], v[164:167], v[6:9]
	v_mfma_f32_16x16x32_bf16 v[2:5], v[172:175], v[164:167], v[2:5]
	s_setprio 0
	s_add_i32 s14, s14, 0x80
	s_add_i32 s13, s13, 2
	s_waitcnt vmcnt(0)
	s_barrier
	s_cmp_lt_u32 s13, 14
	s_cbranch_scc1 .Lglds_12468
	s_waitcnt vmcnt(0)
	v_or_b32_e32 v170, s12, v119
	v_add_lshl_u32 v98, v118, s11, 10
	v_readlane_b32 s12, v254, 8
	v_readlane_b32 s13, v254, 9
	v_readlane_b32 s14, v254, 10
	v_readlane_b32 s15, v254, 11
	v_readlane_b32 s16, v254, 12
	v_readlane_b32 s17, v254, 13
	v_readlane_b32 s18, v254, 14
	v_readlane_b32 s19, v254, 15
	v_readlane_b32 s20, v254, 16
	v_readlane_b32 s21, v254, 17
	v_readlane_b32 s22, v254, 18
	v_readlane_b32 s23, v254, 19
	v_readlane_b32 s24, v254, 20
	v_readlane_b32 s25, v254, 21
	v_readlane_b32 s26, v254, 22
	v_readlane_b32 s27, v254, 23
	v_lshlrev_b32_e32 v168, 2, v170
	v_mov_b32_e32 v169, v99
	v_lshlrev_b64 v[174:175], 2, v[98:99]
	v_lshl_add_u64 v[152:153], s[12:13], 0, v[174:175]
	v_lshl_add_u64 v[160:161], s[82:83], 0, v[174:175]
	v_lshl_add_u64 v[152:153], v[152:153], 0, v[168:169]
	v_lshl_add_u64 v[160:161], v[160:161], 0, v[168:169]
	global_load_dwordx4 v[120:123], v[152:153], off
	global_load_dwordx4 v[124:127], v[152:153], off offset:64
	global_load_dwordx4 v[128:131], v[152:153], off offset:128
	global_load_dwordx4 v[132:135], v[152:153], off offset:192
	v_or_b32_e32 v172, 0x4000, v98
	v_mov_b32_e32 v173, v99
	v_lshlrev_b64 v[174:175], 2, v[172:173]
	v_lshl_add_u64 v[154:155], s[12:13], 0, v[174:175]
	v_lshl_add_u64 v[162:163], s[82:83], 0, v[174:175]
	v_lshl_add_u64 v[154:155], v[154:155], 0, v[168:169]
	v_lshl_add_u64 v[162:163], v[162:163], 0, v[168:169]
	global_load_dwordx4 v[136:139], v[154:155], off
	global_load_dwordx4 v[140:143], v[154:155], off offset:64
	global_load_dwordx4 v[144:147], v[154:155], off offset:128
	global_load_dwordx4 v[148:151], v[154:155], off offset:192
	v_or_b32_e32 v172, 0x8000, v98
	v_mov_b32_e32 v173, v99
	v_lshlrev_b64 v[174:175], 2, v[172:173]
	v_lshl_add_u64 v[156:157], s[12:13], 0, v[174:175]
	v_lshl_add_u64 v[164:165], s[82:83], 0, v[174:175]
	v_lshl_add_u64 v[156:157], v[156:157], 0, v[168:169]
	v_lshl_add_u64 v[164:165], v[164:165], 0, v[168:169]
	global_load_dwordx4 v[22:25], v[156:157], off
	global_load_dwordx4 v[26:29], v[156:157], off offset:64
	global_load_dwordx4 v[42:45], v[156:157], off offset:128
	global_load_dwordx4 v[46:49], v[156:157], off offset:192
	v_or_b32_e32 v172, 0xc000, v98
	v_mov_b32_e32 v173, v99
	v_lshlrev_b64 v[174:175], 2, v[172:173]
	v_lshl_add_u64 v[158:159], s[12:13], 0, v[174:175]
	v_lshl_add_u64 v[166:167], s[82:83], 0, v[174:175]
	v_lshl_add_u64 v[158:159], v[158:159], 0, v[168:169]
	v_lshl_add_u64 v[166:167], v[166:167], 0, v[168:169]
	global_load_dwordx4 v[50:53], v[158:159], off
	global_load_dwordx4 v[54:57], v[158:159], off offset:64
	global_load_dwordx4 v[58:61], v[158:159], off offset:128
	global_load_dwordx4 v[70:73], v[158:159], off offset:192
	s_waitcnt vmcnt(15)
	v_pk_fma_f32 v[120:121], v[120:121], s[6:7], v[94:95] op_sel_hi:[1,0,1]
	v_pk_fma_f32 v[122:123], v[122:123], s[6:7], v[96:97] op_sel_hi:[1,0,1]
	s_waitcnt vmcnt(14)
	v_pk_fma_f32 v[124:125], v[124:125], s[6:7], v[90:91] op_sel_hi:[1,0,1]
	v_pk_fma_f32 v[126:127], v[126:127], s[6:7], v[92:93] op_sel_hi:[1,0,1]
	s_waitcnt vmcnt(13)
	v_pk_fma_f32 v[128:129], v[128:129], s[6:7], v[86:87] op_sel_hi:[1,0,1]
	v_pk_fma_f32 v[130:131], v[130:131], s[6:7], v[88:89] op_sel_hi:[1,0,1]
	s_waitcnt vmcnt(12)
	v_pk_fma_f32 v[132:133], v[132:133], s[6:7], v[82:83] op_sel_hi:[1,0,1]
	v_pk_fma_f32 v[134:135], v[134:135], s[6:7], v[84:85] op_sel_hi:[1,0,1]
	s_waitcnt vmcnt(11)
	v_pk_fma_f32 v[136:137], v[136:137], s[6:7], v[78:79] op_sel_hi:[1,0,1]
	v_pk_fma_f32 v[138:139], v[138:139], s[6:7], v[80:81] op_sel_hi:[1,0,1]
	s_waitcnt vmcnt(10)
	v_pk_fma_f32 v[140:141], v[140:141], s[6:7], v[74:75] op_sel_hi:[1,0,1]
	v_pk_fma_f32 v[142:143], v[142:143], s[6:7], v[76:77] op_sel_hi:[1,0,1]
	s_waitcnt vmcnt(9)
	v_pk_fma_f32 v[144:145], v[144:145], s[6:7], v[62:63] op_sel_hi:[1,0,1]
	v_pk_fma_f32 v[146:147], v[146:147], s[6:7], v[64:65] op_sel_hi:[1,0,1]
	s_waitcnt vmcnt(8)
	v_pk_fma_f32 v[148:149], v[148:149], s[6:7], v[30:31] op_sel_hi:[1,0,1]
	v_pk_fma_f32 v[150:151], v[150:151], s[6:7], v[32:33] op_sel_hi:[1,0,1]
	s_waitcnt vmcnt(7)
	v_pk_fma_f32 v[22:23], v[22:23], s[6:7], v[66:67] op_sel_hi:[1,0,1]
	v_pk_fma_f32 v[24:25], v[24:25], s[6:7], v[68:69] op_sel_hi:[1,0,1]
	s_waitcnt vmcnt(6)
	v_pk_fma_f32 v[26:27], v[26:27], s[6:7], v[38:39] op_sel_hi:[1,0,1]
	v_pk_fma_f32 v[28:29], v[28:29], s[6:7], v[40:41] op_sel_hi:[1,0,1]
	s_waitcnt vmcnt(5)
	v_pk_fma_f32 v[42:43], v[42:43], s[6:7], v[34:35] op_sel_hi:[1,0,1]
	v_pk_fma_f32 v[44:45], v[44:45], s[6:7], v[36:37] op_sel_hi:[1,0,1]
	s_waitcnt vmcnt(4)
	v_pk_fma_f32 v[46:47], v[46:47], s[6:7], v[18:19] op_sel_hi:[1,0,1]
	v_pk_fma_f32 v[48:49], v[48:49], s[6:7], v[20:21] op_sel_hi:[1,0,1]
	s_waitcnt vmcnt(3)
	v_pk_fma_f32 v[50:51], v[50:51], s[6:7], v[14:15] op_sel_hi:[1,0,1]
	v_pk_fma_f32 v[52:53], v[52:53], s[6:7], v[16:17] op_sel_hi:[1,0,1]
	s_waitcnt vmcnt(2)
	v_pk_fma_f32 v[54:55], v[54:55], s[6:7], v[10:11] op_sel_hi:[1,0,1]
	v_pk_fma_f32 v[56:57], v[56:57], s[6:7], v[12:13] op_sel_hi:[1,0,1]
	s_waitcnt vmcnt(1)
	v_pk_fma_f32 v[58:59], v[58:59], s[6:7], v[6:7] op_sel_hi:[1,0,1]
	v_pk_fma_f32 v[60:61], v[60:61], s[6:7], v[8:9] op_sel_hi:[1,0,1]
	s_waitcnt vmcnt(0)
	v_pk_fma_f32 v[70:71], v[70:71], s[6:7], v[2:3] op_sel_hi:[1,0,1]
	v_pk_fma_f32 v[72:73], v[72:73], s[6:7], v[4:5] op_sel_hi:[1,0,1]
	global_store_dwordx4 v[160:161], v[120:123], off
	global_store_dwordx4 v[160:161], v[124:127], off offset:64
	global_store_dwordx4 v[160:161], v[128:131], off offset:128
	global_store_dwordx4 v[160:161], v[132:135], off offset:192
	global_store_dwordx4 v[162:163], v[136:139], off
	global_store_dwordx4 v[162:163], v[140:143], off offset:64
	global_store_dwordx4 v[162:163], v[144:147], off offset:128
	global_store_dwordx4 v[162:163], v[148:151], off offset:192
	global_store_dwordx4 v[164:165], v[22:25], off
	global_store_dwordx4 v[164:165], v[26:29], off offset:64
	global_store_dwordx4 v[164:165], v[42:45], off offset:128
	global_store_dwordx4 v[164:165], v[46:49], off offset:192
	global_store_dwordx4 v[166:167], v[50:53], off
	global_store_dwordx4 v[166:167], v[54:57], off offset:64
	global_store_dwordx4 v[166:167], v[58:61], off offset:128
	global_store_dwordx4 v[166:167], v[70:73], off offset:192
	s_add_i32 s7, s7, s3
	s_cmpk_lt_u32 s7, 0x100
	s_cbranch_scc1 .LBB0_422

.LBB0_518:
	s_lshr_b32 s4, s6, 1
	s_and_b32 s4, s4, 0xf8
	s_or_b32 s4, s4, s2
	s_lshl_b32 s10, s4, 7
	s_lshl_b32 s4, s6, 7
	v_or_b32_e32 v2, s10, v1
	s_and_b32 s11, s4, 0x780
	v_lshlrev_b32_e32 v98, 10, v2
	v_lshl_add_u64 v[104:105], v[100:101], 0, v[98:99]
	v_or_b32_e32 v2, s11, v1
	v_lshlrev_b32_e32 v98, 10, v2
	v_lshl_add_u64 v[108:109], v[102:103], 0, v[98:99]
	v_and_b32_e32 v177, 7, v106
	v_bfe_u32 v176, v106, 3, 3
	v_xor_b32_e32 v176, v177, v176
	v_sub_u32_e32 v176, v176, v177
	v_lshlrev_b32_e32 v176, 4, v176
	v_ashrrev_i32_e32 v177, 31, v176
	v_lshrrev_b32_e32 v182, 6, v106
	v_mov_b32_e32 v183, 0x110
	v_lshl_add_u32 v182, v182, 10, v183
	v_lshl_add_u64 v[184:185], v[104:105], 0, v[176:177]
	v_lshl_add_u64 v[192:193], v[108:109], 0, v[176:177]
	v_readfirstlane_b32 s14, v182
	v_add_co_u32_e32 v186, vcc, s7, v184
	v_addc_co_u32_e32 v187, vcc, 0, v185, vcc
	v_add_co_u32_e32 v188, vcc, s8, v184
	v_addc_co_u32_e32 v189, vcc, 0, v185, vcc
	v_add_co_u32_e32 v190, vcc, s9, v184
	v_addc_co_u32_e32 v191, vcc, 0, v185, vcc
	v_add_co_u32_e32 v194, vcc, s7, v192
	v_addc_co_u32_e32 v195, vcc, 0, v193, vcc
	v_add_co_u32_e32 v196, vcc, s8, v192
	v_addc_co_u32_e32 v197, vcc, 0, v193, vcc
	v_add_co_u32_e32 v198, vcc, s9, v192
	v_addc_co_u32_e32 v199, vcc, 0, v193, vcc
	v_mov_b32_e32 v30, 0
	v_mov_b32_e32 v31, v99
	v_mov_b32_e32 v32, v99
	v_mov_b32_e32 v33, v99
	v_mov_b32_e32 v38, 0
	v_mov_b32_e32 v39, v99
	v_mov_b32_e32 v40, v99
	v_mov_b32_e32 v41, v99
	v_mov_b32_e32 v50, 0
	v_mov_b32_e32 v51, v99
	v_mov_b32_e32 v52, v99
	v_mov_b32_e32 v53, v99
	v_mov_b32_e32 v74, 0
	v_mov_b32_e32 v75, v99
	v_mov_b32_e32 v76, v99
	v_mov_b32_e32 v77, v99
	v_mov_b32_e32 v82, 0
	v_mov_b32_e32 v83, v99
	v_mov_b32_e32 v84, v99
	v_mov_b32_e32 v85, v99
	v_mov_b32_e32 v86, 0
	v_mov_b32_e32 v87, v99
	v_mov_b32_e32 v88, v99
	v_mov_b32_e32 v89, v99
	v_mov_b32_e32 v90, 0
	v_mov_b32_e32 v91, v99
	v_mov_b32_e32 v92, v99
	v_mov_b32_e32 v93, v99
	v_mov_b32_e32 v94, 0
	v_mov_b32_e32 v95, v99
	v_mov_b32_e32 v96, v99
	v_mov_b32_e32 v97, v99
	v_mov_b32_e32 v34, 0
	v_mov_b32_e32 v35, v99
	v_mov_b32_e32 v36, v99
	v_mov_b32_e32 v37, v99
	v_mov_b32_e32 v26, 0
	v_mov_b32_e32 v27, v99
	v_mov_b32_e32 v28, v99
	v_mov_b32_e32 v29, v99
	v_mov_b32_e32 v22, 0
	v_mov_b32_e32 v23, v99
	v_mov_b32_e32 v24, v99
	v_mov_b32_e32 v25, v99
	v_mov_b32_e32 v18, 0
	v_mov_b32_e32 v19, v99
	v_mov_b32_e32 v20, v99
	v_mov_b32_e32 v21, v99
	v_mov_b32_e32 v14, 0
	v_mov_b32_e32 v15, v99
	v_mov_b32_e32 v16, v99
	v_mov_b32_e32 v17, v99
	v_mov_b32_e32 v10, 0
	v_mov_b32_e32 v11, v99
	v_mov_b32_e32 v12, v99
	v_mov_b32_e32 v13, v99
	v_mov_b32_e32 v6, 0
	v_mov_b32_e32 v7, v99
	v_mov_b32_e32 v8, v99
	v_mov_b32_e32 v9, v99
	v_mov_b32_e32 v2, 0
	v_mov_b32_e32 v3, v99
	v_mov_b32_e32 v4, v99
	v_mov_b32_e32 v5, v99
	s_add_u32 m0, s14, 0x0
	s_nop 0
	global_load_lds_dwordx4 v[184:185], off
	s_add_u32 m0, s14, 0x1000
	s_nop 0
	global_load_lds_dwordx4 v[186:187], off
	s_add_u32 m0, s14, 0x2000
	s_nop 0
	global_load_lds_dwordx4 v[188:189], off
	s_add_u32 m0, s14, 0x3000
	s_nop 0
	global_load_lds_dwordx4 v[190:191], off
	s_add_u32 m0, s14, 0x4000
	s_nop 0
	global_load_lds_dwordx4 v[192:193], off
	s_add_u32 m0, s14, 0x5000
	s_nop 0
	global_load_lds_dwordx4 v[194:195], off
	s_add_u32 m0, s14, 0x6000
	s_nop 0
	global_load_lds_dwordx4 v[196:197], off
	s_add_u32 m0, s14, 0x7000
	s_nop 0
	global_load_lds_dwordx4 v[198:199], off
	s_mov_b32 s13, 0
	s_mov_b32 s12, -2
	s_waitcnt vmcnt(0)
	s_barrier
.Lglds_14401:
	s_add_i32 s4, s13, 0x40
	s_lshl_b32 s4, s4, 1
	s_add_u32 m0, s14, 0x8000
	v_lshl_add_u64 v[200:201], v[184:185], 0, s[4:5]
	global_load_lds_dwordx4 v[200:201], off
	s_add_u32 m0, s14, 0x9000
	v_lshl_add_u64 v[202:203], v[186:187], 0, s[4:5]
	global_load_lds_dwordx4 v[202:203], off
	s_add_u32 m0, s14, 0xa000
	v_lshl_add_u64 v[200:201], v[188:189], 0, s[4:5]
	global_load_lds_dwordx4 v[200:201], off
	s_add_u32 m0, s14, 0xb000
	v_lshl_add_u64 v[202:203], v[190:191], 0, s[4:5]
	global_load_lds_dwordx4 v[202:203], off
	s_add_u32 m0, s14, 0xc000
	v_lshl_add_u64 v[200:201], v[192:193], 0, s[4:5]
	global_load_lds_dwordx4 v[200:201], off
	s_add_u32 m0, s14, 0xd000
	v_lshl_add_u64 v[202:203], v[194:195], 0, s[4:5]
	global_load_lds_dwordx4 v[202:203], off
	s_add_u32 m0, s14, 0xe000
	v_lshl_add_u64 v[200:201], v[196:197], 0, s[4:5]
	global_load_lds_dwordx4 v[200:201], off
	s_add_u32 m0, s14, 0xf000
	v_lshl_add_u64 v[202:203], v[198:199], 0, s[4:5]
	global_load_lds_dwordx4 v[202:203], off
	s_setprio 1
	ds_read_b128 v[152:155], v112 offset:16384
	ds_read_b128 v[156:159], v112 offset:18432
	ds_read_b128 v[160:163], v110
	ds_read_b128 v[164:167], v110 offset:2048
	ds_read_b128 v[168:171], v112 offset:20480
	ds_read_b128 v[172:175], v113 offset:16384
	s_waitcnt lgkmcnt(3)
	v_mfma_i32_16x16x64_i8 v[94:97], v[152:155], v[160:163], v[94:97]
	v_mfma_i32_16x16x64_i8 v[90:93], v[156:159], v[160:163], v[90:93]
	s_waitcnt lgkmcnt(1)
	v_mfma_i32_16x16x64_i8 v[86:89], v[168:171], v[160:163], v[86:89]
	s_waitcnt lgkmcnt(0)
	v_mfma_i32_16x16x64_i8 v[82:85], v[172:175], v[160:163], v[82:85]
	v_mfma_i32_16x16x64_i8 v[74:77], v[152:155], v[164:167], v[74:77]
	v_mfma_i32_16x16x64_i8 v[50:53], v[156:159], v[164:167], v[50:53]
	v_mfma_i32_16x16x64_i8 v[38:41], v[168:171], v[164:167], v[38:41]
	v_mfma_i32_16x16x64_i8 v[30:33], v[172:175], v[164:167], v[30:33]
	ds_read_b128 v[160:163], v110 offset:4096
	ds_read_b128 v[164:167], v111
	s_waitcnt lgkmcnt(1)
	v_mfma_i32_16x16x64_i8 v[34:37], v[152:155], v[160:163], v[34:37]
	v_mfma_i32_16x16x64_i8 v[26:29], v[156:159], v[160:163], v[26:29]
	v_mfma_i32_16x16x64_i8 v[22:25], v[168:171], v[160:163], v[22:25]
	v_mfma_i32_16x16x64_i8 v[18:21], v[172:175], v[160:163], v[18:21]
	s_waitcnt lgkmcnt(0)
	v_mfma_i32_16x16x64_i8 v[14:17], v[152:155], v[164:167], v[14:17]
	ds_read_b128 v[152:155], v116 offset:16384
	v_mfma_i32_16x16x64_i8 v[10:13], v[156:159], v[164:167], v[10:13]
	v_mfma_i32_16x16x64_i8 v[6:9], v[168:171], v[164:167], v[6:9]
	v_mfma_i32_16x16x64_i8 v[2:5], v[172:175], v[164:167], v[2:5]
	ds_read_b128 v[156:159], v116 offset:18432
	ds_read_b128 v[160:163], v114
	ds_read_b128 v[164:167], v114 offset:2048
	ds_read_b128 v[168:171], v116 offset:20480
	ds_read_b128 v[172:175], v117 offset:16384
	s_waitcnt lgkmcnt(3)
	v_mfma_i32_16x16x64_i8 v[94:97], v[152:155], v[160:163], v[94:97]
	v_mfma_i32_16x16x64_i8 v[90:93], v[156:159], v[160:163], v[90:93]
	s_waitcnt lgkmcnt(1)
	v_mfma_i32_16x16x64_i8 v[86:89], v[168:171], v[160:163], v[86:89]
	s_waitcnt lgkmcnt(0)
	v_mfma_i32_16x16x64_i8 v[82:85], v[172:175], v[160:163], v[82:85]
	v_mfma_i32_16x16x64_i8 v[74:77], v[152:155], v[164:167], v[74:77]
	v_mfma_i32_16x16x64_i8 v[50:53], v[156:159], v[164:167], v[50:53]
	v_mfma_i32_16x16x64_i8 v[38:41], v[168:171], v[164:167], v[38:41]
	v_mfma_i32_16x16x64_i8 v[30:33], v[172:175], v[164:167], v[30:33]
	ds_read_b128 v[160:163], v114 offset:4096
	ds_read_b128 v[164:167], v115
	s_waitcnt lgkmcnt(1)
	v_mfma_i32_16x16x64_i8 v[34:37], v[152:155], v[160:163], v[34:37]
	v_mfma_i32_16x16x64_i8 v[26:29], v[156:159], v[160:163], v[26:29]
	v_mfma_i32_16x16x64_i8 v[22:25], v[168:171], v[160:163], v[22:25]
	v_mfma_i32_16x16x64_i8 v[18:21], v[172:175], v[160:163], v[18:21]
	s_waitcnt lgkmcnt(0)
	v_mfma_i32_16x16x64_i8 v[14:17], v[152:155], v[164:167], v[14:17]
	v_mfma_i32_16x16x64_i8 v[10:13], v[156:159], v[164:167], v[10:13]
	v_mfma_i32_16x16x64_i8 v[6:9], v[168:171], v[164:167], v[6:9]
	v_mfma_i32_16x16x64_i8 v[2:5], v[172:175], v[164:167], v[2:5]
	s_setprio 0
	s_waitcnt vmcnt(0)
	s_barrier
	s_add_i32 s4, s13, 0x80
	s_min_u32 s4, s4, 0x1c0
	s_lshl_b32 s4, s4, 1
	s_add_u32 m0, s14, 0x0
	v_lshl_add_u64 v[200:201], v[184:185], 0, s[4:5]
	global_load_lds_dwordx4 v[200:201], off
	s_add_u32 m0, s14, 0x1000
	v_lshl_add_u64 v[202:203], v[186:187], 0, s[4:5]
	global_load_lds_dwordx4 v[202:203], off
	s_add_u32 m0, s14, 0x2000
	v_lshl_add_u64 v[200:201], v[188:189], 0, s[4:5]
	global_load_lds_dwordx4 v[200:201], off
	s_add_u32 m0, s14, 0x3000
	v_lshl_add_u64 v[202:203], v[190:191], 0, s[4:5]
	global_load_lds_dwordx4 v[202:203], off
	s_add_u32 m0, s14, 0x4000
	v_lshl_add_u64 v[200:201], v[192:193], 0, s[4:5]
	global_load_lds_dwordx4 v[200:201], off
	s_add_u32 m0, s14, 0x5000
	v_lshl_add_u64 v[202:203], v[194:195], 0, s[4:5]
	global_load_lds_dwordx4 v[202:203], off
	s_add_u32 m0, s14, 0x6000
	v_lshl_add_u64 v[200:201], v[196:197], 0, s[4:5]
	global_load_lds_dwordx4 v[200:201], off
	s_add_u32 m0, s14, 0x7000
	v_lshl_add_u64 v[202:203], v[198:199], 0, s[4:5]
	global_load_lds_dwordx4 v[202:203], off
	s_setprio 1
	ds_read_b128 v[152:155], v112 offset:49152
	ds_read_b128 v[156:159], v112 offset:51200
	ds_read_b128 v[160:163], v110 offset:32768
	ds_read_b128 v[164:167], v110 offset:34816
	ds_read_b128 v[168:171], v112 offset:53248
	ds_read_b128 v[172:175], v113 offset:49152
	s_waitcnt lgkmcnt(3)
	v_mfma_i32_16x16x64_i8 v[94:97], v[152:155], v[160:163], v[94:97]
	v_mfma_i32_16x16x64_i8 v[90:93], v[156:159], v[160:163], v[90:93]
	s_waitcnt lgkmcnt(1)
	v_mfma_i32_16x16x64_i8 v[86:89], v[168:171], v[160:163], v[86:89]
	s_waitcnt lgkmcnt(0)
	v_mfma_i32_16x16x64_i8 v[82:85], v[172:175], v[160:163], v[82:85]
	v_mfma_i32_16x16x64_i8 v[74:77], v[152:155], v[164:167], v[74:77]
	v_mfma_i32_16x16x64_i8 v[50:53], v[156:159], v[164:167], v[50:53]
	v_mfma_i32_16x16x64_i8 v[38:41], v[168:171], v[164:167], v[38:41]
	v_mfma_i32_16x16x64_i8 v[30:33], v[172:175], v[164:167], v[30:33]
	ds_read_b128 v[160:163], v110 offset:36864
	ds_read_b128 v[164:167], v111 offset:32768
	s_waitcnt lgkmcnt(1)
	v_mfma_i32_16x16x64_i8 v[34:37], v[152:155], v[160:163], v[34:37]
	v_mfma_i32_16x16x64_i8 v[26:29], v[156:159], v[160:163], v[26:29]
	v_mfma_i32_16x16x64_i8 v[22:25], v[168:171], v[160:163], v[22:25]
	v_mfma_i32_16x16x64_i8 v[18:21], v[172:175], v[160:163], v[18:21]
	s_waitcnt lgkmcnt(0)
	v_mfma_i32_16x16x64_i8 v[14:17], v[152:155], v[164:167], v[14:17]
	ds_read_b128 v[152:155], v116 offset:49152
	v_mfma_i32_16x16x64_i8 v[10:13], v[156:159], v[164:167], v[10:13]
	v_mfma_i32_16x16x64_i8 v[6:9], v[168:171], v[164:167], v[6:9]
	v_mfma_i32_16x16x64_i8 v[2:5], v[172:175], v[164:167], v[2:5]
	ds_read_b128 v[156:159], v116 offset:51200
	ds_read_b128 v[160:163], v114 offset:32768
	ds_read_b128 v[164:167], v114 offset:34816
	ds_read_b128 v[168:171], v116 offset:53248
	ds_read_b128 v[172:175], v117 offset:49152
	s_waitcnt lgkmcnt(3)
	v_mfma_i32_16x16x64_i8 v[94:97], v[152:155], v[160:163], v[94:97]
	v_mfma_i32_16x16x64_i8 v[90:93], v[156:159], v[160:163], v[90:93]
	s_waitcnt lgkmcnt(1)
	v_mfma_i32_16x16x64_i8 v[86:89], v[168:171], v[160:163], v[86:89]
	s_waitcnt lgkmcnt(0)
	v_mfma_i32_16x16x64_i8 v[82:85], v[172:175], v[160:163], v[82:85]
	v_mfma_i32_16x16x64_i8 v[74:77], v[152:155], v[164:167], v[74:77]
	v_mfma_i32_16x16x64_i8 v[50:53], v[156:159], v[164:167], v[50:53]
	v_mfma_i32_16x16x64_i8 v[38:41], v[168:171], v[164:167], v[38:41]
	v_mfma_i32_16x16x64_i8 v[30:33], v[172:175], v[164:167], v[30:33]
	ds_read_b128 v[160:163], v114 offset:36864
	ds_read_b128 v[164:167], v115 offset:32768
	s_waitcnt lgkmcnt(1)
	v_mfma_i32_16x16x64_i8 v[34:37], v[152:155], v[160:163], v[34:37]
	v_mfma_i32_16x16x64_i8 v[26:29], v[156:159], v[160:163], v[26:29]
	v_mfma_i32_16x16x64_i8 v[22:25], v[168:171], v[160:163], v[22:25]
	v_mfma_i32_16x16x64_i8 v[18:21], v[172:175], v[160:163], v[18:21]
	s_waitcnt lgkmcnt(0)
	v_mfma_i32_16x16x64_i8 v[14:17], v[152:155], v[164:167], v[14:17]
	v_mfma_i32_16x16x64_i8 v[10:13], v[156:159], v[164:167], v[10:13]
	v_mfma_i32_16x16x64_i8 v[6:9], v[168:171], v[164:167], v[6:9]
	v_mfma_i32_16x16x64_i8 v[2:5], v[172:175], v[164:167], v[2:5]
	s_setprio 0
	s_add_i32 s13, s13, 0x80
	s_add_i32 s12, s12, 2
	s_waitcnt vmcnt(0)
	s_barrier
	s_cmp_lt_u32 s12, 6
	s_cbranch_scc1 .Lglds_14401
	v_cvt_f32_i32_e32 v94, v94
	v_cvt_f32_i32_e32 v95, v95
	v_cvt_f32_i32_e32 v96, v96
	v_cvt_f32_i32_e32 v97, v97
	v_cvt_f32_i32_e32 v90, v90
	v_cvt_f32_i32_e32 v91, v91
	v_cvt_f32_i32_e32 v92, v92
	v_cvt_f32_i32_e32 v93, v93
	v_cvt_f32_i32_e32 v86, v86
	v_cvt_f32_i32_e32 v87, v87
	v_cvt_f32_i32_e32 v88, v88
	v_cvt_f32_i32_e32 v89, v89
	v_cvt_f32_i32_e32 v82, v82
	v_cvt_f32_i32_e32 v83, v83
	v_cvt_f32_i32_e32 v84, v84
	v_cvt_f32_i32_e32 v85, v85
	v_cvt_f32_i32_e32 v74, v74
	v_cvt_f32_i32_e32 v75, v75
	v_cvt_f32_i32_e32 v76, v76
	v_cvt_f32_i32_e32 v77, v77
	v_cvt_f32_i32_e32 v50, v50
	v_cvt_f32_i32_e32 v51, v51
	v_cvt_f32_i32_e32 v52, v52
	v_cvt_f32_i32_e32 v53, v53
	v_cvt_f32_i32_e32 v38, v38
	v_cvt_f32_i32_e32 v39, v39
	v_cvt_f32_i32_e32 v40, v40
	v_cvt_f32_i32_e32 v41, v41
	v_cvt_f32_i32_e32 v30, v30
	v_cvt_f32_i32_e32 v31, v31
	v_cvt_f32_i32_e32 v32, v32
	v_cvt_f32_i32_e32 v33, v33
	v_cvt_f32_i32_e32 v34, v34
	v_cvt_f32_i32_e32 v35, v35
	v_cvt_f32_i32_e32 v36, v36
	v_cvt_f32_i32_e32 v37, v37
	v_cvt_f32_i32_e32 v26, v26
	v_cvt_f32_i32_e32 v27, v27
	v_cvt_f32_i32_e32 v28, v28
	v_cvt_f32_i32_e32 v29, v29
	v_cvt_f32_i32_e32 v22, v22
	v_cvt_f32_i32_e32 v23, v23
	v_cvt_f32_i32_e32 v24, v24
	v_cvt_f32_i32_e32 v25, v25
	v_cvt_f32_i32_e32 v18, v18
	v_cvt_f32_i32_e32 v19, v19
	v_cvt_f32_i32_e32 v20, v20
	v_cvt_f32_i32_e32 v21, v21
	v_cvt_f32_i32_e32 v14, v14
	v_cvt_f32_i32_e32 v15, v15
	v_cvt_f32_i32_e32 v16, v16
	v_cvt_f32_i32_e32 v17, v17
	v_cvt_f32_i32_e32 v10, v10
	v_cvt_f32_i32_e32 v11, v11
	v_cvt_f32_i32_e32 v12, v12
	v_cvt_f32_i32_e32 v13, v13
	v_cvt_f32_i32_e32 v6, v6
	v_cvt_f32_i32_e32 v7, v7
	v_cvt_f32_i32_e32 v8, v8
	v_cvt_f32_i32_e32 v9, v9
	v_cvt_f32_i32_e32 v2, v2
	v_cvt_f32_i32_e32 v3, v3
	v_cvt_f32_i32_e32 v4, v4
	v_cvt_f32_i32_e32 v5, v5
	s_waitcnt vmcnt(0)
	v_add_u32_e32 v98, s10, v118
	v_or_b32_e32 v146, s11, v119
	v_lshl_add_u64 v[144:145], v[98:99], 2, s[68:69]
	v_lshlrev_b32_e32 v148, 2, v146
	global_load_dword v136, v[144:145], off
	global_load_dword v138, v[144:145], off offset:64
	global_load_dword v140, v[144:145], off offset:128
	global_load_dword v142, v[144:145], off offset:192
	global_load_dwordx4 v[120:123], v148, s[74:75]
	global_load_dwordx4 v[124:127], v148, s[74:75] offset:64
	global_load_dwordx4 v[128:131], v148, s[74:75] offset:128
	global_load_dwordx4 v[132:135], v148, s[74:75] offset:192
	v_lshlrev_b32_e32 v146, 1, v146
	v_mov_b32_e32 v147, v99
	v_lshlrev_b64 v[42:43], 12, v[98:99]
	v_lshl_add_u64 v[42:43], s[64:65], 0, v[42:43]
	v_lshl_add_u64 v[42:43], v[42:43], 0, v[146:147]
	v_or_b32_e32 v54, 16, v98
	v_mov_b32_e32 v55, v99
	v_lshlrev_b64 v[44:45], 12, v[54:55]
	v_lshl_add_u64 v[44:45], s[64:65], 0, v[44:45]
	v_lshl_add_u64 v[44:45], v[44:45], 0, v[146:147]
	v_or_b32_e32 v54, 32, v98
	v_mov_b32_e32 v55, v99
	v_lshlrev_b64 v[46:47], 12, v[54:55]
	v_lshl_add_u64 v[46:47], s[64:65], 0, v[46:47]
	v_lshl_add_u64 v[46:47], v[46:47], 0, v[146:147]
	v_or_b32_e32 v54, 48, v98
	v_mov_b32_e32 v55, v99
	v_lshlrev_b64 v[48:49], 12, v[54:55]
	v_lshl_add_u64 v[48:49], s[64:65], 0, v[48:49]
	v_lshl_add_u64 v[48:49], v[48:49], 0, v[146:147]
	s_waitcnt vmcnt(0)
	v_pk_mul_f32 v[94:95], v[136:137], v[94:95] op_sel_hi:[0,1]
	v_pk_mul_f32 v[96:97], v[136:137], v[96:97] op_sel_hi:[0,1]
	v_pk_mul_f32 v[94:95], v[120:121], v[94:95]
	v_pk_mul_f32 v[96:97], v[96:97], v[122:123]
	v_cvt_pk_bf16_f32 v94, v94, v95
	v_cvt_pk_bf16_f32 v95, v96, v97
	global_store_dwordx2 v[42:43], v[94:95], off
	v_pk_mul_f32 v[90:91], v[136:137], v[90:91] op_sel_hi:[0,1]
	v_pk_mul_f32 v[92:93], v[136:137], v[92:93] op_sel_hi:[0,1]
	v_pk_mul_f32 v[90:91], v[124:125], v[90:91]
	v_pk_mul_f32 v[92:93], v[92:93], v[126:127]
	v_cvt_pk_bf16_f32 v90, v90, v91
	v_cvt_pk_bf16_f32 v91, v92, v93
	global_store_dwordx2 v[42:43], v[90:91], off offset:32
	v_pk_mul_f32 v[86:87], v[136:137], v[86:87] op_sel_hi:[0,1]
	v_pk_mul_f32 v[88:89], v[136:137], v[88:89] op_sel_hi:[0,1]
	v_pk_mul_f32 v[86:87], v[128:129], v[86:87]
	v_pk_mul_f32 v[88:89], v[88:89], v[130:131]
	v_cvt_pk_bf16_f32 v86, v86, v87
	v_cvt_pk_bf16_f32 v87, v88, v89
	global_store_dwordx2 v[42:43], v[86:87], off offset:64
	v_pk_mul_f32 v[82:83], v[136:137], v[82:83] op_sel_hi:[0,1]
	v_pk_mul_f32 v[84:85], v[136:137], v[84:85] op_sel_hi:[0,1]
	v_pk_mul_f32 v[82:83], v[132:133], v[82:83]
	v_pk_mul_f32 v[84:85], v[84:85], v[134:135]
	v_cvt_pk_bf16_f32 v82, v82, v83
	v_cvt_pk_bf16_f32 v83, v84, v85
	global_store_dwordx2 v[42:43], v[82:83], off offset:96
	v_pk_mul_f32 v[74:75], v[138:139], v[74:75] op_sel_hi:[0,1]
	v_pk_mul_f32 v[76:77], v[138:139], v[76:77] op_sel_hi:[0,1]
	v_pk_mul_f32 v[74:75], v[120:121], v[74:75]
	v_pk_mul_f32 v[76:77], v[76:77], v[122:123]
	v_cvt_pk_bf16_f32 v74, v74, v75
	v_cvt_pk_bf16_f32 v75, v76, v77
	global_store_dwordx2 v[44:45], v[74:75], off
	v_pk_mul_f32 v[50:51], v[138:139], v[50:51] op_sel_hi:[0,1]
	v_pk_mul_f32 v[52:53], v[138:139], v[52:53] op_sel_hi:[0,1]
	v_pk_mul_f32 v[50:51], v[124:125], v[50:51]
	v_pk_mul_f32 v[52:53], v[52:53], v[126:127]
	v_cvt_pk_bf16_f32 v50, v50, v51
	v_cvt_pk_bf16_f32 v51, v52, v53
	global_store_dwordx2 v[44:45], v[50:51], off offset:32
	v_pk_mul_f32 v[38:39], v[138:139], v[38:39] op_sel_hi:[0,1]
	v_pk_mul_f32 v[40:41], v[138:139], v[40:41] op_sel_hi:[0,1]
	v_pk_mul_f32 v[38:39], v[128:129], v[38:39]
	v_pk_mul_f32 v[40:41], v[40:41], v[130:131]
	v_cvt_pk_bf16_f32 v38, v38, v39
	v_cvt_pk_bf16_f32 v39, v40, v41
	global_store_dwordx2 v[44:45], v[38:39], off offset:64
	v_pk_mul_f32 v[30:31], v[138:139], v[30:31] op_sel_hi:[0,1]
	v_pk_mul_f32 v[32:33], v[138:139], v[32:33] op_sel_hi:[0,1]
	v_pk_mul_f32 v[30:31], v[132:133], v[30:31]
	v_pk_mul_f32 v[32:33], v[32:33], v[134:135]
	v_cvt_pk_bf16_f32 v30, v30, v31
	v_cvt_pk_bf16_f32 v31, v32, v33
	global_store_dwordx2 v[44:45], v[30:31], off offset:96
	v_pk_mul_f32 v[34:35], v[140:141], v[34:35] op_sel_hi:[0,1]
	v_pk_mul_f32 v[36:37], v[140:141], v[36:37] op_sel_hi:[0,1]
	v_pk_mul_f32 v[34:35], v[120:121], v[34:35]
	v_pk_mul_f32 v[36:37], v[36:37], v[122:123]
	v_cvt_pk_bf16_f32 v34, v34, v35
	v_cvt_pk_bf16_f32 v35, v36, v37
	global_store_dwordx2 v[46:47], v[34:35], off
	v_pk_mul_f32 v[26:27], v[140:141], v[26:27] op_sel_hi:[0,1]
	v_pk_mul_f32 v[28:29], v[140:141], v[28:29] op_sel_hi:[0,1]
	v_pk_mul_f32 v[26:27], v[124:125], v[26:27]
	v_pk_mul_f32 v[28:29], v[28:29], v[126:127]
	v_cvt_pk_bf16_f32 v26, v26, v27
	v_cvt_pk_bf16_f32 v27, v28, v29
	global_store_dwordx2 v[46:47], v[26:27], off offset:32
	v_pk_mul_f32 v[22:23], v[140:141], v[22:23] op_sel_hi:[0,1]
	v_pk_mul_f32 v[24:25], v[140:141], v[24:25] op_sel_hi:[0,1]
	v_pk_mul_f32 v[22:23], v[128:129], v[22:23]
	v_pk_mul_f32 v[24:25], v[24:25], v[130:131]
	v_cvt_pk_bf16_f32 v22, v22, v23
	v_cvt_pk_bf16_f32 v23, v24, v25
	global_store_dwordx2 v[46:47], v[22:23], off offset:64
	v_pk_mul_f32 v[18:19], v[140:141], v[18:19] op_sel_hi:[0,1]
	v_pk_mul_f32 v[20:21], v[140:141], v[20:21] op_sel_hi:[0,1]
	v_pk_mul_f32 v[18:19], v[132:133], v[18:19]
	v_pk_mul_f32 v[20:21], v[20:21], v[134:135]
	v_cvt_pk_bf16_f32 v18, v18, v19
	v_cvt_pk_bf16_f32 v19, v20, v21
	global_store_dwordx2 v[46:47], v[18:19], off offset:96
	v_pk_mul_f32 v[14:15], v[142:143], v[14:15] op_sel_hi:[0,1]
	v_pk_mul_f32 v[16:17], v[142:143], v[16:17] op_sel_hi:[0,1]
	v_pk_mul_f32 v[14:15], v[120:121], v[14:15]
	v_pk_mul_f32 v[16:17], v[16:17], v[122:123]
	v_cvt_pk_bf16_f32 v14, v14, v15
	v_cvt_pk_bf16_f32 v15, v16, v17
	global_store_dwordx2 v[48:49], v[14:15], off
	v_pk_mul_f32 v[10:11], v[142:143], v[10:11] op_sel_hi:[0,1]
	v_pk_mul_f32 v[12:13], v[142:143], v[12:13] op_sel_hi:[0,1]
	v_pk_mul_f32 v[10:11], v[124:125], v[10:11]
	v_pk_mul_f32 v[12:13], v[12:13], v[126:127]
	v_cvt_pk_bf16_f32 v10, v10, v11
	v_cvt_pk_bf16_f32 v11, v12, v13
	global_store_dwordx2 v[48:49], v[10:11], off offset:32
	v_pk_mul_f32 v[6:7], v[142:143], v[6:7] op_sel_hi:[0,1]
	v_pk_mul_f32 v[8:9], v[142:143], v[8:9] op_sel_hi:[0,1]
	v_pk_mul_f32 v[6:7], v[128:129], v[6:7]
	v_pk_mul_f32 v[8:9], v[8:9], v[130:131]
	v_cvt_pk_bf16_f32 v6, v6, v7
	v_cvt_pk_bf16_f32 v7, v8, v9
	global_store_dwordx2 v[48:49], v[6:7], off offset:64
	v_pk_mul_f32 v[2:3], v[142:143], v[2:3] op_sel_hi:[0,1]
	v_pk_mul_f32 v[4:5], v[142:143], v[4:5] op_sel_hi:[0,1]
	v_pk_mul_f32 v[2:3], v[132:133], v[2:3]
	v_pk_mul_f32 v[4:5], v[4:5], v[134:135]
	v_cvt_pk_bf16_f32 v2, v2, v3
	v_cvt_pk_bf16_f32 v3, v4, v5
	global_store_dwordx2 v[48:49], v[2:3], off offset:96
	s_add_i32 s6, s6, s3
	s_cmpk_lt_u32 s6, 0x200
	s_cbranch_scc1 .LBB0_518

.LBB0_664:
	s_cmpk_lt_u32 s3, 0x1c0
	s_cselect_b32 s4, 1, 2
	s_cselect_b32 s13, 7, 6
	s_cmpk_gt_u32 s3, 0xdf
	s_cselect_b32 s4, s4, 0
	s_mul_i32 s14, s4, 0xff20
	s_add_i32 s16, s14, s3
	s_sext_i32_i16 s14, s16
	v_cvt_f32_ubyte0_e32 v3, s13
	v_cvt_f32_i32_e32 v2, s14
	v_rcp_iflag_f32_e32 v4, v3
	s_ashr_i32 s14, s14, 30
	s_or_b32 s17, s14, 1
	s_mul_i32 s4, s4, 7
	v_mul_f32_e32 v4, v2, v4
	v_trunc_f32_e32 v4, v4
	v_fma_f32 v2, -v4, v3, v2
	v_cvt_i32_f32_e32 v4, v4
	v_cmp_ge_f32_e64 s[14:15], |v2|, v3
	s_and_b64 s[14:15], s[14:15], exec
	s_cselect_b32 s14, s17, 0
	v_readfirstlane_b32 s15, v4
	s_add_i32 s14, s15, s14
	s_sext_i32_i16 s15, s14
	s_mul_i32 s14, s14, s13
	s_sub_i32 s13, s16, s14
	s_sext_i32_i16 s13, s13
	s_add_i32 s4, s4, s13
	s_lshl_b32 s13, s15, 10
	s_or_b32 s13, s13, s6
	v_or_b32_e32 v2, s13, v1
	v_ashrrev_i32_e32 v3, 31, v2
	s_lshl_b32 s14, s4, 7
	v_lshlrev_b64 v[2:3], 12, v[2:3]
	v_lshl_add_u64 v[104:105], v[100:101], 0, v[2:3]
	v_or_b32_e32 v2, s14, v1
	v_ashrrev_i32_e32 v3, 31, v2
	v_lshlrev_b64 v[2:3], 11, v[2:3]
	v_add_co_u32_e32 v6, vcc, s7, v104
	v_lshl_add_u64 v[108:109], v[102:103], 0, v[2:3]
	v_and_b32_e32 v181, 7, v106
	v_bfe_u32 v180, v106, 3, 3
	v_xor_b32_e32 v180, v181, v180
	v_sub_u32_e32 v180, v180, v181
	v_lshlrev_b32_e32 v180, 4, v180
	v_ashrrev_i32_e32 v181, 31, v180
	v_lshrrev_b32_e32 v186, 6, v106
	v_mov_b32_e32 v187, 0x110
	v_lshl_add_u32 v186, v186, 10, v187
	v_lshl_add_u64 v[188:189], v[104:105], 0, v[180:181]
	v_lshl_add_u64 v[196:197], v[108:109], 0, v[180:181]
	v_readfirstlane_b32 s17, v186
	v_add_co_u32_e32 v190, vcc, s7, v188
	v_addc_co_u32_e32 v191, vcc, 0, v189, vcc
	v_add_co_u32_e32 v192, vcc, s9, v188
	v_addc_co_u32_e32 v193, vcc, 0, v189, vcc
	v_add_co_u32_e32 v194, vcc, s10, v188
	v_addc_co_u32_e32 v195, vcc, 0, v189, vcc
	v_add_co_u32_e32 v198, vcc, s8, v196
	v_addc_co_u32_e32 v199, vcc, 0, v197, vcc
	v_add_co_u32_e32 v200, vcc, s7, v196
	v_addc_co_u32_e32 v201, vcc, 0, v197, vcc
	v_add_co_u32_e32 v202, vcc, s11, v196
	v_addc_co_u32_e32 v203, vcc, 0, v197, vcc
	v_mov_b32_e32 v34, 0
	v_mov_b32_e32 v35, v99
	v_mov_b32_e32 v36, v99
	v_mov_b32_e32 v37, v99
	v_mov_b32_e32 v38, 0
	v_mov_b32_e32 v39, v99
	v_mov_b32_e32 v40, v99
	v_mov_b32_e32 v41, v99
	v_mov_b32_e32 v42, 0
	v_mov_b32_e32 v43, v99
	v_mov_b32_e32 v44, v99
	v_mov_b32_e32 v45, v99
	v_mov_b32_e32 v54, 0
	v_mov_b32_e32 v55, v99
	v_mov_b32_e32 v56, v99
	v_mov_b32_e32 v57, v99
	v_mov_b32_e32 v82, 0
	v_mov_b32_e32 v83, v99
	v_mov_b32_e32 v84, v99
	v_mov_b32_e32 v85, v99
	v_mov_b32_e32 v86, 0
	v_mov_b32_e32 v87, v99
	v_mov_b32_e32 v88, v99
	v_mov_b32_e32 v89, v99
	v_mov_b32_e32 v90, 0
	v_mov_b32_e32 v91, v99
	v_mov_b32_e32 v92, v99
	v_mov_b32_e32 v93, v99
	v_mov_b32_e32 v94, 0
	v_mov_b32_e32 v95, v99
	v_mov_b32_e32 v96, v99
	v_mov_b32_e32 v97, v99
	v_mov_b32_e32 v78, 0
	v_mov_b32_e32 v79, v99
	v_mov_b32_e32 v80, v99
	v_mov_b32_e32 v81, v99
	v_mov_b32_e32 v74, 0
	v_mov_b32_e32 v75, v99
	v_mov_b32_e32 v76, v99
	v_mov_b32_e32 v77, v99
	v_mov_b32_e32 v70, 0
	v_mov_b32_e32 v71, v99
	v_mov_b32_e32 v72, v99
	v_mov_b32_e32 v73, v99
	v_mov_b32_e32 v66, 0
	v_mov_b32_e32 v67, v99
	v_mov_b32_e32 v68, v99
	v_mov_b32_e32 v69, v99
	v_mov_b32_e32 v62, 0
	v_mov_b32_e32 v63, v99
	v_mov_b32_e32 v64, v99
	v_mov_b32_e32 v65, v99
	v_mov_b32_e32 v58, 0
	v_mov_b32_e32 v59, v99
	v_mov_b32_e32 v60, v99
	v_mov_b32_e32 v61, v99
	v_mov_b32_e32 v50, 0
	v_mov_b32_e32 v51, v99
	v_mov_b32_e32 v52, v99
	v_mov_b32_e32 v53, v99
	v_mov_b32_e32 v46, 0
	v_mov_b32_e32 v47, v99
	v_mov_b32_e32 v48, v99
	v_mov_b32_e32 v49, v99
	s_add_u32 m0, s17, 0x0
	s_nop 0
	global_load_lds_dwordx4 v[188:189], off
	s_add_u32 m0, s17, 0x1000
	s_nop 0
	global_load_lds_dwordx4 v[190:191], off
	s_add_u32 m0, s17, 0x2000
	s_nop 0
	global_load_lds_dwordx4 v[192:193], off
	s_add_u32 m0, s17, 0x3000
	s_nop 0
	global_load_lds_dwordx4 v[194:195], off
	s_add_u32 m0, s17, 0x4000
	s_nop 0
	global_load_lds_dwordx4 v[196:197], off
	s_add_u32 m0, s17, 0x5000
	s_nop 0
	global_load_lds_dwordx4 v[198:199], off
	s_add_u32 m0, s17, 0x6000
	s_nop 0
	global_load_lds_dwordx4 v[200:201], off
	s_add_u32 m0, s17, 0x7000
	s_nop 0
	global_load_lds_dwordx4 v[202:203], off
	s_mov_b32 s16, 0
	s_mov_b32 s15, -2
	s_waitcnt vmcnt(0)
	s_barrier
.Lglds_22142:
	s_add_i32 s4, s16, 0x40
	s_lshl_b32 s4, s4, 1
	s_add_u32 m0, s17, 0x8000
	v_lshl_add_u64 v[204:205], v[188:189], 0, s[4:5]
	global_load_lds_dwordx4 v[204:205], off
	s_add_u32 m0, s17, 0x9000
	v_lshl_add_u64 v[206:207], v[190:191], 0, s[4:5]
	global_load_lds_dwordx4 v[206:207], off
	s_add_u32 m0, s17, 0xa000
	v_lshl_add_u64 v[204:205], v[192:193], 0, s[4:5]
	global_load_lds_dwordx4 v[204:205], off
	s_add_u32 m0, s17, 0xb000
	v_lshl_add_u64 v[206:207], v[194:195], 0, s[4:5]
	global_load_lds_dwordx4 v[206:207], off
	s_add_u32 m0, s17, 0xc000
	v_lshl_add_u64 v[204:205], v[196:197], 0, s[4:5]
	global_load_lds_dwordx4 v[204:205], off
	s_add_u32 m0, s17, 0xd000
	v_lshl_add_u64 v[206:207], v[198:199], 0, s[4:5]
	global_load_lds_dwordx4 v[206:207], off
	s_add_u32 m0, s17, 0xe000
	v_lshl_add_u64 v[204:205], v[200:201], 0, s[4:5]
	global_load_lds_dwordx4 v[204:205], off
	s_add_u32 m0, s17, 0xf000
	v_lshl_add_u64 v[206:207], v[202:203], 0, s[4:5]
	global_load_lds_dwordx4 v[206:207], off
	s_setprio 1
	ds_read_b128 v[152:155], v112 offset:16384
	ds_read_b128 v[156:159], v112 offset:18432
	ds_read_b128 v[160:163], v110
	ds_read_b128 v[164:167], v110 offset:2048
	ds_read_b128 v[168:171], v112 offset:20480
	ds_read_b128 v[172:175], v113 offset:16384
	s_waitcnt lgkmcnt(3)
	v_mfma_f32_16x16x32_bf16 v[94:97], v[152:155], v[160:163], v[94:97]
	v_mfma_f32_16x16x32_bf16 v[90:93], v[156:159], v[160:163], v[90:93]
	s_waitcnt lgkmcnt(1)
	v_mfma_f32_16x16x32_bf16 v[86:89], v[168:171], v[160:163], v[86:89]
	s_waitcnt lgkmcnt(0)
	v_mfma_f32_16x16x32_bf16 v[82:85], v[172:175], v[160:163], v[82:85]
	v_mfma_f32_16x16x32_bf16 v[54:57], v[152:155], v[164:167], v[54:57]
	v_mfma_f32_16x16x32_bf16 v[42:45], v[156:159], v[164:167], v[42:45]
	v_mfma_f32_16x16x32_bf16 v[38:41], v[168:171], v[164:167], v[38:41]
	v_mfma_f32_16x16x32_bf16 v[34:37], v[172:175], v[164:167], v[34:37]
	ds_read_b128 v[160:163], v110 offset:4096
	ds_read_b128 v[164:167], v111
	s_waitcnt lgkmcnt(1)
	v_mfma_f32_16x16x32_bf16 v[78:81], v[152:155], v[160:163], v[78:81]
	v_mfma_f32_16x16x32_bf16 v[74:77], v[156:159], v[160:163], v[74:77]
	v_mfma_f32_16x16x32_bf16 v[70:73], v[168:171], v[160:163], v[70:73]
	v_mfma_f32_16x16x32_bf16 v[66:69], v[172:175], v[160:163], v[66:69]
	s_waitcnt lgkmcnt(0)
	v_mfma_f32_16x16x32_bf16 v[62:65], v[152:155], v[164:167], v[62:65]
	ds_read_b128 v[152:155], v116 offset:16384
	v_mfma_f32_16x16x32_bf16 v[58:61], v[156:159], v[164:167], v[58:61]
	v_mfma_f32_16x16x32_bf16 v[50:53], v[168:171], v[164:167], v[50:53]
	v_mfma_f32_16x16x32_bf16 v[46:49], v[172:175], v[164:167], v[46:49]
	ds_read_b128 v[156:159], v116 offset:18432
	ds_read_b128 v[160:163], v114
	ds_read_b128 v[164:167], v114 offset:2048
	ds_read_b128 v[168:171], v116 offset:20480
	ds_read_b128 v[172:175], v117 offset:16384
	s_waitcnt lgkmcnt(3)
	v_mfma_f32_16x16x32_bf16 v[94:97], v[152:155], v[160:163], v[94:97]
	v_mfma_f32_16x16x32_bf16 v[90:93], v[156:159], v[160:163], v[90:93]
	s_waitcnt lgkmcnt(1)
	v_mfma_f32_16x16x32_bf16 v[86:89], v[168:171], v[160:163], v[86:89]
	s_waitcnt lgkmcnt(0)
	v_mfma_f32_16x16x32_bf16 v[82:85], v[172:175], v[160:163], v[82:85]
	v_mfma_f32_16x16x32_bf16 v[54:57], v[152:155], v[164:167], v[54:57]
	v_mfma_f32_16x16x32_bf16 v[42:45], v[156:159], v[164:167], v[42:45]
	v_mfma_f32_16x16x32_bf16 v[38:41], v[168:171], v[164:167], v[38:41]
	v_mfma_f32_16x16x32_bf16 v[34:37], v[172:175], v[164:167], v[34:37]
	ds_read_b128 v[160:163], v114 offset:4096
	ds_read_b128 v[164:167], v115
	s_waitcnt lgkmcnt(1)
	v_mfma_f32_16x16x32_bf16 v[78:81], v[152:155], v[160:163], v[78:81]
	v_mfma_f32_16x16x32_bf16 v[74:77], v[156:159], v[160:163], v[74:77]
	v_mfma_f32_16x16x32_bf16 v[70:73], v[168:171], v[160:163], v[70:73]
	v_mfma_f32_16x16x32_bf16 v[66:69], v[172:175], v[160:163], v[66:69]
	s_waitcnt lgkmcnt(0)
	v_mfma_f32_16x16x32_bf16 v[62:65], v[152:155], v[164:167], v[62:65]
	v_mfma_f32_16x16x32_bf16 v[58:61], v[156:159], v[164:167], v[58:61]
	v_mfma_f32_16x16x32_bf16 v[50:53], v[168:171], v[164:167], v[50:53]
	v_mfma_f32_16x16x32_bf16 v[46:49], v[172:175], v[164:167], v[46:49]
	s_setprio 0
	s_waitcnt vmcnt(0)
	s_barrier
	s_add_i32 s4, s16, 0x80
	s_min_u32 s4, s4, 0x3c0
	s_lshl_b32 s4, s4, 1
	s_add_u32 m0, s17, 0x0
	v_lshl_add_u64 v[204:205], v[188:189], 0, s[4:5]
	global_load_lds_dwordx4 v[204:205], off
	s_add_u32 m0, s17, 0x1000
	v_lshl_add_u64 v[206:207], v[190:191], 0, s[4:5]
	global_load_lds_dwordx4 v[206:207], off
	s_add_u32 m0, s17, 0x2000
	v_lshl_add_u64 v[204:205], v[192:193], 0, s[4:5]
	global_load_lds_dwordx4 v[204:205], off
	s_add_u32 m0, s17, 0x3000
	v_lshl_add_u64 v[206:207], v[194:195], 0, s[4:5]
	global_load_lds_dwordx4 v[206:207], off
	s_add_u32 m0, s17, 0x4000
	v_lshl_add_u64 v[204:205], v[196:197], 0, s[4:5]
	global_load_lds_dwordx4 v[204:205], off
	s_add_u32 m0, s17, 0x5000
	v_lshl_add_u64 v[206:207], v[198:199], 0, s[4:5]
	global_load_lds_dwordx4 v[206:207], off
	s_add_u32 m0, s17, 0x6000
	v_lshl_add_u64 v[204:205], v[200:201], 0, s[4:5]
	global_load_lds_dwordx4 v[204:205], off
	s_add_u32 m0, s17, 0x7000
	v_lshl_add_u64 v[206:207], v[202:203], 0, s[4:5]
	global_load_lds_dwordx4 v[206:207], off
	s_setprio 1
	ds_read_b128 v[152:155], v112 offset:49152
	ds_read_b128 v[156:159], v112 offset:51200
	ds_read_b128 v[160:163], v110 offset:32768
	ds_read_b128 v[164:167], v110 offset:34816
	ds_read_b128 v[168:171], v112 offset:53248
	ds_read_b128 v[172:175], v113 offset:49152
	s_waitcnt lgkmcnt(3)
	v_mfma_f32_16x16x32_bf16 v[94:97], v[152:155], v[160:163], v[94:97]
	v_mfma_f32_16x16x32_bf16 v[90:93], v[156:159], v[160:163], v[90:93]
	s_waitcnt lgkmcnt(1)
	v_mfma_f32_16x16x32_bf16 v[86:89], v[168:171], v[160:163], v[86:89]
	s_waitcnt lgkmcnt(0)
	v_mfma_f32_16x16x32_bf16 v[82:85], v[172:175], v[160:163], v[82:85]
	v_mfma_f32_16x16x32_bf16 v[54:57], v[152:155], v[164:167], v[54:57]
	v_mfma_f32_16x16x32_bf16 v[42:45], v[156:159], v[164:167], v[42:45]
	v_mfma_f32_16x16x32_bf16 v[38:41], v[168:171], v[164:167], v[38:41]
	v_mfma_f32_16x16x32_bf16 v[34:37], v[172:175], v[164:167], v[34:37]
	ds_read_b128 v[160:163], v110 offset:36864
	ds_read_b128 v[164:167], v111 offset:32768
	s_waitcnt lgkmcnt(1)
	v_mfma_f32_16x16x32_bf16 v[78:81], v[152:155], v[160:163], v[78:81]
	v_mfma_f32_16x16x32_bf16 v[74:77], v[156:159], v[160:163], v[74:77]
	v_mfma_f32_16x16x32_bf16 v[70:73], v[168:171], v[160:163], v[70:73]
	v_mfma_f32_16x16x32_bf16 v[66:69], v[172:175], v[160:163], v[66:69]
	s_waitcnt lgkmcnt(0)
	v_mfma_f32_16x16x32_bf16 v[62:65], v[152:155], v[164:167], v[62:65]
	ds_read_b128 v[152:155], v116 offset:49152
	v_mfma_f32_16x16x32_bf16 v[58:61], v[156:159], v[164:167], v[58:61]
	v_mfma_f32_16x16x32_bf16 v[50:53], v[168:171], v[164:167], v[50:53]
	v_mfma_f32_16x16x32_bf16 v[46:49], v[172:175], v[164:167], v[46:49]
	ds_read_b128 v[156:159], v116 offset:51200
	ds_read_b128 v[160:163], v114 offset:32768
	ds_read_b128 v[164:167], v114 offset:34816
	ds_read_b128 v[168:171], v116 offset:53248
	ds_read_b128 v[172:175], v117 offset:49152
	s_waitcnt lgkmcnt(3)
	v_mfma_f32_16x16x32_bf16 v[94:97], v[152:155], v[160:163], v[94:97]
	v_mfma_f32_16x16x32_bf16 v[90:93], v[156:159], v[160:163], v[90:93]
	s_waitcnt lgkmcnt(1)
	v_mfma_f32_16x16x32_bf16 v[86:89], v[168:171], v[160:163], v[86:89]
	s_waitcnt lgkmcnt(0)
	v_mfma_f32_16x16x32_bf16 v[82:85], v[172:175], v[160:163], v[82:85]
	v_mfma_f32_16x16x32_bf16 v[54:57], v[152:155], v[164:167], v[54:57]
	v_mfma_f32_16x16x32_bf16 v[42:45], v[156:159], v[164:167], v[42:45]
	v_mfma_f32_16x16x32_bf16 v[38:41], v[168:171], v[164:167], v[38:41]
	v_mfma_f32_16x16x32_bf16 v[34:37], v[172:175], v[164:167], v[34:37]
	ds_read_b128 v[160:163], v114 offset:36864
	ds_read_b128 v[164:167], v115 offset:32768
	s_waitcnt lgkmcnt(1)
	v_mfma_f32_16x16x32_bf16 v[78:81], v[152:155], v[160:163], v[78:81]
	v_mfma_f32_16x16x32_bf16 v[74:77], v[156:159], v[160:163], v[74:77]
	v_mfma_f32_16x16x32_bf16 v[70:73], v[168:171], v[160:163], v[70:73]
	v_mfma_f32_16x16x32_bf16 v[66:69], v[172:175], v[160:163], v[66:69]
	s_waitcnt lgkmcnt(0)
	v_mfma_f32_16x16x32_bf16 v[62:65], v[152:155], v[164:167], v[62:65]
	v_mfma_f32_16x16x32_bf16 v[58:61], v[156:159], v[164:167], v[58:61]
	v_mfma_f32_16x16x32_bf16 v[50:53], v[168:171], v[164:167], v[50:53]
	v_mfma_f32_16x16x32_bf16 v[46:49], v[172:175], v[164:167], v[46:49]
	s_setprio 0
	s_add_i32 s16, s16, 0x80
	s_add_i32 s15, s15, 2
	s_waitcnt vmcnt(0)
	s_barrier
	s_cmp_lt_u32 s15, 14
	s_cbranch_scc1 .Lglds_22142
	s_waitcnt vmcnt(7)
	v_or_b32_e32 v2, s14, v119
	s_waitcnt vmcnt(5)
	v_add_u32_e32 v10, s13, v118
	v_mov_b64_e32 v[4:5], s[64:65]
	v_ashrrev_i32_e32 v3, 31, v2
	v_mad_i64_i32 v[6:7], s[14:15], v10, s12, v[4:5]
	v_lshlrev_b64 v[2:3], 1, v[2:3]
	v_lshl_add_u64 v[6:7], v[6:7], 0, v[2:3]
	v_cvt_pk_bf16_f32 v8, v94, v95
	v_cvt_pk_bf16_f32 v9, v96, v97
	global_store_dwordx2 v[6:7], v[8:9], off
	v_cvt_pk_bf16_f32 v8, v90, v91
	v_cvt_pk_bf16_f32 v9, v92, v93
	global_store_dwordx2 v[6:7], v[8:9], off offset:32
	v_cvt_pk_bf16_f32 v8, v86, v87
	v_cvt_pk_bf16_f32 v9, v88, v89
	global_store_dwordx2 v[6:7], v[8:9], off offset:64
	v_cvt_pk_bf16_f32 v8, v82, v83
	v_cvt_pk_bf16_f32 v9, v84, v85
	global_store_dwordx2 v[6:7], v[8:9], off offset:96
	v_or_b32_e32 v6, 16, v10
	v_mad_i64_i32 v[6:7], s[14:15], v6, s12, v[4:5]
	v_lshl_add_u64 v[6:7], v[6:7], 0, v[2:3]
	v_cvt_pk_bf16_f32 v8, v54, v55
	v_cvt_pk_bf16_f32 v9, v56, v57
	global_store_dwordx2 v[6:7], v[8:9], off
	v_cvt_pk_bf16_f32 v8, v42, v43
	v_cvt_pk_bf16_f32 v9, v44, v45
	global_store_dwordx2 v[6:7], v[8:9], off offset:32
	v_cvt_pk_bf16_f32 v8, v38, v39
	v_cvt_pk_bf16_f32 v9, v40, v41
	global_store_dwordx2 v[6:7], v[8:9], off offset:64
	v_cvt_pk_bf16_f32 v8, v34, v35
	v_cvt_pk_bf16_f32 v9, v36, v37
	global_store_dwordx2 v[6:7], v[8:9], off offset:96
	v_or_b32_e32 v6, 32, v10
	v_mad_i64_i32 v[6:7], s[14:15], v6, s12, v[4:5]
	v_lshl_add_u64 v[6:7], v[6:7], 0, v[2:3]
	v_cvt_pk_bf16_f32 v8, v78, v79
	v_cvt_pk_bf16_f32 v9, v80, v81
	global_store_dwordx2 v[6:7], v[8:9], off
	v_cvt_pk_bf16_f32 v8, v74, v75
	v_cvt_pk_bf16_f32 v9, v76, v77
	global_store_dwordx2 v[6:7], v[8:9], off offset:32
	v_cvt_pk_bf16_f32 v8, v70, v71
	v_cvt_pk_bf16_f32 v9, v72, v73
	global_store_dwordx2 v[6:7], v[8:9], off offset:64
	v_cvt_pk_bf16_f32 v8, v66, v67
	v_cvt_pk_bf16_f32 v9, v68, v69
	global_store_dwordx2 v[6:7], v[8:9], off offset:96
	v_or_b32_e32 v6, 48, v10
	v_mad_i64_i32 v[4:5], s[14:15], v6, s12, v[4:5]
	v_lshl_add_u64 v[2:3], v[4:5], 0, v[2:3]
	v_cvt_pk_bf16_f32 v4, v62, v63
	v_cvt_pk_bf16_f32 v5, v64, v65
	global_store_dwordx2 v[2:3], v[4:5], off
	v_cvt_pk_bf16_f32 v4, v58, v59
	v_cvt_pk_bf16_f32 v5, v60, v61
	global_store_dwordx2 v[2:3], v[4:5], off offset:32
	v_cvt_pk_bf16_f32 v4, v50, v51
	v_cvt_pk_bf16_f32 v5, v52, v53
	s_add_i32 s3, s3, s2
	global_store_dwordx2 v[2:3], v[4:5], off offset:64
	v_cvt_pk_bf16_f32 v4, v46, v47
	v_cvt_pk_bf16_f32 v5, v48, v49
	s_cmpk_lt_u32 s3, 0x280
	global_store_dwordx2 v[2:3], v[4:5], off offset:96
	s_cbranch_scc1 .LBB0_664

.LBB0_798:
	s_and_b32 s4, s7, 0xf8
	s_or_b32 s4, s4, s2
	s_lshl_b32 s11, s4, 7
	s_lshl_b32 s4, s7, 7
	v_or_b32_e32 v0, s11, v107
	s_and_b32 s12, s4, 0x380
	v_lshlrev_b32_e32 v96, 11, v0
	v_lshl_add_u64 v[102:103], v[100:101], 0, v[96:97]
	v_or_b32_e32 v0, s12, v107
	v_lshlrev_b32_e32 v96, 11, v0
	v_lshl_add_u64 v[104:105], v[98:99], 0, v[96:97]
	v_and_b32_e32 v181, 7, v106
	v_bfe_u32 v180, v106, 3, 3
	v_xor_b32_e32 v180, v181, v180
	v_sub_u32_e32 v180, v180, v181
	v_lshlrev_b32_e32 v180, 4, v180
	v_ashrrev_i32_e32 v181, 31, v180
	v_lshrrev_b32_e32 v186, 6, v106
	v_mov_b32_e32 v187, 0x110
	v_lshl_add_u32 v186, v186, 10, v187
	v_lshl_add_u64 v[188:189], v[102:103], 0, v[180:181]
	v_lshl_add_u64 v[196:197], v[104:105], 0, v[180:181]
	v_readfirstlane_b32 s15, v186
	v_add_co_u32_e32 v190, vcc, s8, v188
	v_addc_co_u32_e32 v191, vcc, 0, v189, vcc
	v_add_co_u32_e32 v192, vcc, s9, v188
	v_addc_co_u32_e32 v193, vcc, 0, v189, vcc
	v_add_co_u32_e32 v194, vcc, s10, v188
	v_addc_co_u32_e32 v195, vcc, 0, v189, vcc
	v_add_co_u32_e32 v198, vcc, s8, v196
	v_addc_co_u32_e32 v199, vcc, 0, v197, vcc
	v_add_co_u32_e32 v200, vcc, s9, v196
	v_addc_co_u32_e32 v201, vcc, 0, v197, vcc
	v_add_co_u32_e32 v202, vcc, s10, v196
	v_addc_co_u32_e32 v203, vcc, 0, v197, vcc
	v_mov_b32_e32 v28, 0
	v_mov_b32_e32 v29, v97
	v_mov_b32_e32 v30, v97
	v_mov_b32_e32 v31, v97
	v_mov_b32_e32 v60, 0
	v_mov_b32_e32 v61, v97
	v_mov_b32_e32 v62, v97
	v_mov_b32_e32 v63, v97
	v_mov_b32_e32 v72, 0
	v_mov_b32_e32 v73, v97
	v_mov_b32_e32 v74, v97
	v_mov_b32_e32 v75, v97
	v_mov_b32_e32 v76, 0
	v_mov_b32_e32 v77, v97
	v_mov_b32_e32 v78, v97
	v_mov_b32_e32 v79, v97
	v_mov_b32_e32 v80, 0
	v_mov_b32_e32 v81, v97
	v_mov_b32_e32 v82, v97
	v_mov_b32_e32 v83, v97
	v_mov_b32_e32 v84, 0
	v_mov_b32_e32 v85, v97
	v_mov_b32_e32 v86, v97
	v_mov_b32_e32 v87, v97
	v_mov_b32_e32 v88, 0
	v_mov_b32_e32 v89, v97
	v_mov_b32_e32 v90, v97
	v_mov_b32_e32 v91, v97
	v_mov_b32_e32 v92, 0
	v_mov_b32_e32 v93, v97
	v_mov_b32_e32 v94, v97
	v_mov_b32_e32 v95, v97
	v_mov_b32_e32 v64, 0
	v_mov_b32_e32 v65, v97
	v_mov_b32_e32 v66, v97
	v_mov_b32_e32 v67, v97
	v_mov_b32_e32 v36, 0
	v_mov_b32_e32 v37, v97
	v_mov_b32_e32 v38, v97
	v_mov_b32_e32 v39, v97
	v_mov_b32_e32 v32, 0
	v_mov_b32_e32 v33, v97
	v_mov_b32_e32 v34, v97
	v_mov_b32_e32 v35, v97
	v_mov_b32_e32 v16, 0
	v_mov_b32_e32 v17, v97
	v_mov_b32_e32 v18, v97
	v_mov_b32_e32 v19, v97
	v_mov_b32_e32 v12, 0
	v_mov_b32_e32 v13, v97
	v_mov_b32_e32 v14, v97
	v_mov_b32_e32 v15, v97
	v_mov_b32_e32 v8, 0
	v_mov_b32_e32 v9, v97
	v_mov_b32_e32 v10, v97
	v_mov_b32_e32 v11, v97
	v_mov_b32_e32 v4, 0
	v_mov_b32_e32 v5, v97
	v_mov_b32_e32 v6, v97
	v_mov_b32_e32 v7, v97
	v_mov_b32_e32 v0, 0
	v_mov_b32_e32 v1, v97
	v_mov_b32_e32 v2, v97
	v_mov_b32_e32 v3, v97
	s_add_u32 m0, s15, 0x0
	s_nop 0
	global_load_lds_dwordx4 v[188:189], off
	s_add_u32 m0, s15, 0x1000
	s_nop 0
	global_load_lds_dwordx4 v[190:191], off
	s_add_u32 m0, s15, 0x2000
	s_nop 0
	global_load_lds_dwordx4 v[192:193], off
	s_add_u32 m0, s15, 0x3000
	s_nop 0
	global_load_lds_dwordx4 v[194:195], off
	s_add_u32 m0, s15, 0x4000
	s_nop 0
	global_load_lds_dwordx4 v[196:197], off
	s_add_u32 m0, s15, 0x5000
	s_nop 0
	global_load_lds_dwordx4 v[198:199], off
	s_add_u32 m0, s15, 0x6000
	s_nop 0
	global_load_lds_dwordx4 v[200:201], off
	s_add_u32 m0, s15, 0x7000
	s_nop 0
	global_load_lds_dwordx4 v[202:203], off
	s_mov_b32 s14, 0
	s_mov_b32 s13, -2
	s_waitcnt vmcnt(0)
	s_barrier
.Lglds_26323:
	s_add_i32 s4, s14, 0x40
	s_lshl_b32 s4, s4, 1
	s_add_u32 m0, s15, 0x8000
	v_lshl_add_u64 v[204:205], v[188:189], 0, s[4:5]
	global_load_lds_dwordx4 v[204:205], off
	s_add_u32 m0, s15, 0x9000
	v_lshl_add_u64 v[206:207], v[190:191], 0, s[4:5]
	global_load_lds_dwordx4 v[206:207], off
	s_add_u32 m0, s15, 0xa000
	v_lshl_add_u64 v[204:205], v[192:193], 0, s[4:5]
	global_load_lds_dwordx4 v[204:205], off
	s_add_u32 m0, s15, 0xb000
	v_lshl_add_u64 v[206:207], v[194:195], 0, s[4:5]
	global_load_lds_dwordx4 v[206:207], off
	s_add_u32 m0, s15, 0xc000
	v_lshl_add_u64 v[204:205], v[196:197], 0, s[4:5]
	global_load_lds_dwordx4 v[204:205], off
	s_add_u32 m0, s15, 0xd000
	v_lshl_add_u64 v[206:207], v[198:199], 0, s[4:5]
	global_load_lds_dwordx4 v[206:207], off
	s_add_u32 m0, s15, 0xe000
	v_lshl_add_u64 v[204:205], v[200:201], 0, s[4:5]
	global_load_lds_dwordx4 v[204:205], off
	s_add_u32 m0, s15, 0xf000
	v_lshl_add_u64 v[206:207], v[202:203], 0, s[4:5]
	global_load_lds_dwordx4 v[206:207], off
	s_setprio 1
	ds_read_b128 v[152:155], v111 offset:16384
	ds_read_b128 v[156:159], v111 offset:18432
	ds_read_b128 v[160:163], v109
	ds_read_b128 v[164:167], v109 offset:2048
	ds_read_b128 v[168:171], v111 offset:20480
	ds_read_b128 v[172:175], v112 offset:16384
	s_waitcnt lgkmcnt(3)
	v_mfma_f32_16x16x32_bf16 v[92:95], v[152:155], v[160:163], v[92:95]
	v_mfma_f32_16x16x32_bf16 v[88:91], v[156:159], v[160:163], v[88:91]
	s_waitcnt lgkmcnt(1)
	v_mfma_f32_16x16x32_bf16 v[84:87], v[168:171], v[160:163], v[84:87]
	s_waitcnt lgkmcnt(0)
	v_mfma_f32_16x16x32_bf16 v[80:83], v[172:175], v[160:163], v[80:83]
	v_mfma_f32_16x16x32_bf16 v[76:79], v[152:155], v[164:167], v[76:79]
	v_mfma_f32_16x16x32_bf16 v[72:75], v[156:159], v[164:167], v[72:75]
	v_mfma_f32_16x16x32_bf16 v[60:63], v[168:171], v[164:167], v[60:63]
	v_mfma_f32_16x16x32_bf16 v[28:31], v[172:175], v[164:167], v[28:31]
	ds_read_b128 v[160:163], v109 offset:4096
	ds_read_b128 v[164:167], v110
	s_waitcnt lgkmcnt(1)
	v_mfma_f32_16x16x32_bf16 v[64:67], v[152:155], v[160:163], v[64:67]
	v_mfma_f32_16x16x32_bf16 v[36:39], v[156:159], v[160:163], v[36:39]
	v_mfma_f32_16x16x32_bf16 v[32:35], v[168:171], v[160:163], v[32:35]
	v_mfma_f32_16x16x32_bf16 v[16:19], v[172:175], v[160:163], v[16:19]
	s_waitcnt lgkmcnt(0)
	v_mfma_f32_16x16x32_bf16 v[12:15], v[152:155], v[164:167], v[12:15]
	ds_read_b128 v[152:155], v115 offset:16384
	v_mfma_f32_16x16x32_bf16 v[8:11], v[156:159], v[164:167], v[8:11]
	v_mfma_f32_16x16x32_bf16 v[4:7], v[168:171], v[164:167], v[4:7]
	v_mfma_f32_16x16x32_bf16 v[0:3], v[172:175], v[164:167], v[0:3]
	ds_read_b128 v[156:159], v115 offset:18432
	ds_read_b128 v[160:163], v113
	ds_read_b128 v[164:167], v113 offset:2048
	ds_read_b128 v[168:171], v115 offset:20480
	ds_read_b128 v[172:175], v116 offset:16384
	s_waitcnt lgkmcnt(3)
	v_mfma_f32_16x16x32_bf16 v[92:95], v[152:155], v[160:163], v[92:95]
	v_mfma_f32_16x16x32_bf16 v[88:91], v[156:159], v[160:163], v[88:91]
	s_waitcnt lgkmcnt(1)
	v_mfma_f32_16x16x32_bf16 v[84:87], v[168:171], v[160:163], v[84:87]
	s_waitcnt lgkmcnt(0)
	v_mfma_f32_16x16x32_bf16 v[80:83], v[172:175], v[160:163], v[80:83]
	v_mfma_f32_16x16x32_bf16 v[76:79], v[152:155], v[164:167], v[76:79]
	v_mfma_f32_16x16x32_bf16 v[72:75], v[156:159], v[164:167], v[72:75]
	v_mfma_f32_16x16x32_bf16 v[60:63], v[168:171], v[164:167], v[60:63]
	v_mfma_f32_16x16x32_bf16 v[28:31], v[172:175], v[164:167], v[28:31]
	ds_read_b128 v[160:163], v113 offset:4096
	ds_read_b128 v[164:167], v114
	s_waitcnt lgkmcnt(1)
	v_mfma_f32_16x16x32_bf16 v[64:67], v[152:155], v[160:163], v[64:67]
	v_mfma_f32_16x16x32_bf16 v[36:39], v[156:159], v[160:163], v[36:39]
	v_mfma_f32_16x16x32_bf16 v[32:35], v[168:171], v[160:163], v[32:35]
	v_mfma_f32_16x16x32_bf16 v[16:19], v[172:175], v[160:163], v[16:19]
	s_waitcnt lgkmcnt(0)
	v_mfma_f32_16x16x32_bf16 v[12:15], v[152:155], v[164:167], v[12:15]
	v_mfma_f32_16x16x32_bf16 v[8:11], v[156:159], v[164:167], v[8:11]
	v_mfma_f32_16x16x32_bf16 v[4:7], v[168:171], v[164:167], v[4:7]
	v_mfma_f32_16x16x32_bf16 v[0:3], v[172:175], v[164:167], v[0:3]
	s_setprio 0
	s_waitcnt vmcnt(0)
	s_barrier
	s_add_i32 s4, s14, 0x80
	s_min_u32 s4, s4, 0x3c0
	s_lshl_b32 s4, s4, 1
	s_add_u32 m0, s15, 0x0
	v_lshl_add_u64 v[204:205], v[188:189], 0, s[4:5]
	global_load_lds_dwordx4 v[204:205], off
	s_add_u32 m0, s15, 0x1000
	v_lshl_add_u64 v[206:207], v[190:191], 0, s[4:5]
	global_load_lds_dwordx4 v[206:207], off
	s_add_u32 m0, s15, 0x2000
	v_lshl_add_u64 v[204:205], v[192:193], 0, s[4:5]
	global_load_lds_dwordx4 v[204:205], off
	s_add_u32 m0, s15, 0x3000
	v_lshl_add_u64 v[206:207], v[194:195], 0, s[4:5]
	global_load_lds_dwordx4 v[206:207], off
	s_add_u32 m0, s15, 0x4000
	v_lshl_add_u64 v[204:205], v[196:197], 0, s[4:5]
	global_load_lds_dwordx4 v[204:205], off
	s_add_u32 m0, s15, 0x5000
	v_lshl_add_u64 v[206:207], v[198:199], 0, s[4:5]
	global_load_lds_dwordx4 v[206:207], off
	s_add_u32 m0, s15, 0x6000
	v_lshl_add_u64 v[204:205], v[200:201], 0, s[4:5]
	global_load_lds_dwordx4 v[204:205], off
	s_add_u32 m0, s15, 0x7000
	v_lshl_add_u64 v[206:207], v[202:203], 0, s[4:5]
	global_load_lds_dwordx4 v[206:207], off
	s_setprio 1
	ds_read_b128 v[152:155], v111 offset:49152
	ds_read_b128 v[156:159], v111 offset:51200
	ds_read_b128 v[160:163], v109 offset:32768
	ds_read_b128 v[164:167], v109 offset:34816
	ds_read_b128 v[168:171], v111 offset:53248
	ds_read_b128 v[172:175], v112 offset:49152
	s_waitcnt lgkmcnt(3)
	v_mfma_f32_16x16x32_bf16 v[92:95], v[152:155], v[160:163], v[92:95]
	v_mfma_f32_16x16x32_bf16 v[88:91], v[156:159], v[160:163], v[88:91]
	s_waitcnt lgkmcnt(1)
	v_mfma_f32_16x16x32_bf16 v[84:87], v[168:171], v[160:163], v[84:87]
	s_waitcnt lgkmcnt(0)
	v_mfma_f32_16x16x32_bf16 v[80:83], v[172:175], v[160:163], v[80:83]
	v_mfma_f32_16x16x32_bf16 v[76:79], v[152:155], v[164:167], v[76:79]
	v_mfma_f32_16x16x32_bf16 v[72:75], v[156:159], v[164:167], v[72:75]
	v_mfma_f32_16x16x32_bf16 v[60:63], v[168:171], v[164:167], v[60:63]
	v_mfma_f32_16x16x32_bf16 v[28:31], v[172:175], v[164:167], v[28:31]
	ds_read_b128 v[160:163], v109 offset:36864
	ds_read_b128 v[164:167], v110 offset:32768
	s_waitcnt lgkmcnt(1)
	v_mfma_f32_16x16x32_bf16 v[64:67], v[152:155], v[160:163], v[64:67]
	v_mfma_f32_16x16x32_bf16 v[36:39], v[156:159], v[160:163], v[36:39]
	v_mfma_f32_16x16x32_bf16 v[32:35], v[168:171], v[160:163], v[32:35]
	v_mfma_f32_16x16x32_bf16 v[16:19], v[172:175], v[160:163], v[16:19]
	s_waitcnt lgkmcnt(0)
	v_mfma_f32_16x16x32_bf16 v[12:15], v[152:155], v[164:167], v[12:15]
	ds_read_b128 v[152:155], v115 offset:49152
	v_mfma_f32_16x16x32_bf16 v[8:11], v[156:159], v[164:167], v[8:11]
	v_mfma_f32_16x16x32_bf16 v[4:7], v[168:171], v[164:167], v[4:7]
	v_mfma_f32_16x16x32_bf16 v[0:3], v[172:175], v[164:167], v[0:3]
	ds_read_b128 v[156:159], v115 offset:51200
	ds_read_b128 v[160:163], v113 offset:32768
	ds_read_b128 v[164:167], v113 offset:34816
	ds_read_b128 v[168:171], v115 offset:53248
	ds_read_b128 v[172:175], v116 offset:49152
	s_waitcnt lgkmcnt(3)
	v_mfma_f32_16x16x32_bf16 v[92:95], v[152:155], v[160:163], v[92:95]
	v_mfma_f32_16x16x32_bf16 v[88:91], v[156:159], v[160:163], v[88:91]
	s_waitcnt lgkmcnt(1)
	v_mfma_f32_16x16x32_bf16 v[84:87], v[168:171], v[160:163], v[84:87]
	s_waitcnt lgkmcnt(0)
	v_mfma_f32_16x16x32_bf16 v[80:83], v[172:175], v[160:163], v[80:83]
	v_mfma_f32_16x16x32_bf16 v[76:79], v[152:155], v[164:167], v[76:79]
	v_mfma_f32_16x16x32_bf16 v[72:75], v[156:159], v[164:167], v[72:75]
	v_mfma_f32_16x16x32_bf16 v[60:63], v[168:171], v[164:167], v[60:63]
	v_mfma_f32_16x16x32_bf16 v[28:31], v[172:175], v[164:167], v[28:31]
	ds_read_b128 v[160:163], v113 offset:36864
	ds_read_b128 v[164:167], v114 offset:32768
	s_waitcnt lgkmcnt(1)
	v_mfma_f32_16x16x32_bf16 v[64:67], v[152:155], v[160:163], v[64:67]
	v_mfma_f32_16x16x32_bf16 v[36:39], v[156:159], v[160:163], v[36:39]
	v_mfma_f32_16x16x32_bf16 v[32:35], v[168:171], v[160:163], v[32:35]
	v_mfma_f32_16x16x32_bf16 v[16:19], v[172:175], v[160:163], v[16:19]
	s_waitcnt lgkmcnt(0)
	v_mfma_f32_16x16x32_bf16 v[12:15], v[152:155], v[164:167], v[12:15]
	v_mfma_f32_16x16x32_bf16 v[8:11], v[156:159], v[164:167], v[8:11]
	v_mfma_f32_16x16x32_bf16 v[4:7], v[168:171], v[164:167], v[4:7]
	v_mfma_f32_16x16x32_bf16 v[0:3], v[172:175], v[164:167], v[0:3]
	s_setprio 0
	s_add_i32 s14, s14, 0x80
	s_add_i32 s13, s13, 2
	s_waitcnt vmcnt(0)
	s_barrier
	s_cmp_lt_u32 s13, 14
	s_cbranch_scc1 .Lglds_26323
	s_waitcnt vmcnt(0)
	v_or_b32_e32 v170, s12, v118
	v_add_lshl_u32 v96, v117, s11, 10
	v_readlane_b32 s12, v254, 24
	v_readlane_b32 s16, v254, 28
	v_readlane_b32 s17, v254, 29
	v_readlane_b32 s13, v254, 25
	v_readlane_b32 s14, v254, 26
	v_readlane_b32 s15, v254, 27
	v_readlane_b32 s18, v254, 30
	v_readlane_b32 s19, v254, 31
	v_readlane_b32 s20, v254, 32
	v_readlane_b32 s21, v254, 33
	v_readlane_b32 s22, v254, 34
	v_readlane_b32 s23, v254, 35
	v_readlane_b32 s24, v254, 36
	v_readlane_b32 s25, v254, 37
	v_readlane_b32 s26, v254, 38
	v_readlane_b32 s27, v254, 39
	v_lshlrev_b32_e32 v168, 2, v170
	v_mov_b32_e32 v169, v97
	v_lshlrev_b64 v[174:175], 2, v[96:97]
	v_lshl_add_u64 v[152:153], s[16:17], 0, v[174:175]
	v_lshl_add_u64 v[160:161], s[82:83], 0, v[174:175]
	v_lshl_add_u64 v[152:153], v[152:153], 0, v[168:169]
	v_lshl_add_u64 v[160:161], v[160:161], 0, v[168:169]
	global_load_dwordx4 v[120:123], v[152:153], off
	global_load_dwordx4 v[124:127], v[152:153], off offset:64
	global_load_dwordx4 v[128:131], v[152:153], off offset:128
	global_load_dwordx4 v[132:135], v[152:153], off offset:192
	v_or_b32_e32 v172, 0x4000, v96
	v_mov_b32_e32 v173, v97
	v_lshlrev_b64 v[174:175], 2, v[172:173]
	v_lshl_add_u64 v[154:155], s[16:17], 0, v[174:175]
	v_lshl_add_u64 v[162:163], s[82:83], 0, v[174:175]
	v_lshl_add_u64 v[154:155], v[154:155], 0, v[168:169]
	v_lshl_add_u64 v[162:163], v[162:163], 0, v[168:169]
	global_load_dwordx4 v[136:139], v[154:155], off
	global_load_dwordx4 v[140:143], v[154:155], off offset:64
	global_load_dwordx4 v[144:147], v[154:155], off offset:128
	global_load_dwordx4 v[148:151], v[154:155], off offset:192
	v_or_b32_e32 v172, 0x8000, v96
	v_mov_b32_e32 v173, v97
	v_lshlrev_b64 v[174:175], 2, v[172:173]
	v_lshl_add_u64 v[156:157], s[16:17], 0, v[174:175]
	v_lshl_add_u64 v[164:165], s[82:83], 0, v[174:175]
	v_lshl_add_u64 v[156:157], v[156:157], 0, v[168:169]
	v_lshl_add_u64 v[164:165], v[164:165], 0, v[168:169]
	global_load_dwordx4 v[20:23], v[156:157], off
	global_load_dwordx4 v[24:27], v[156:157], off offset:64
	global_load_dwordx4 v[40:43], v[156:157], off offset:128
	global_load_dwordx4 v[44:47], v[156:157], off offset:192
	v_or_b32_e32 v172, 0xc000, v96
	v_mov_b32_e32 v173, v97
	v_lshlrev_b64 v[174:175], 2, v[172:173]
	v_lshl_add_u64 v[158:159], s[16:17], 0, v[174:175]
	v_lshl_add_u64 v[166:167], s[82:83], 0, v[174:175]
	v_lshl_add_u64 v[158:159], v[158:159], 0, v[168:169]
	v_lshl_add_u64 v[166:167], v[166:167], 0, v[168:169]
	global_load_dwordx4 v[48:51], v[158:159], off
	global_load_dwordx4 v[52:55], v[158:159], off offset:64
	global_load_dwordx4 v[56:59], v[158:159], off offset:128
	global_load_dwordx4 v[68:71], v[158:159], off offset:192
	s_waitcnt vmcnt(15)
	v_pk_fma_f32 v[120:121], v[120:121], s[6:7], v[92:93] op_sel_hi:[1,0,1]
	v_pk_fma_f32 v[122:123], v[122:123], s[6:7], v[94:95] op_sel_hi:[1,0,1]
	s_waitcnt vmcnt(14)
	v_pk_fma_f32 v[124:125], v[124:125], s[6:7], v[88:89] op_sel_hi:[1,0,1]
	v_pk_fma_f32 v[126:127], v[126:127], s[6:7], v[90:91] op_sel_hi:[1,0,1]
	s_waitcnt vmcnt(13)
	v_pk_fma_f32 v[128:129], v[128:129], s[6:7], v[84:85] op_sel_hi:[1,0,1]
	v_pk_fma_f32 v[130:131], v[130:131], s[6:7], v[86:87] op_sel_hi:[1,0,1]
	s_waitcnt vmcnt(12)
	v_pk_fma_f32 v[132:133], v[132:133], s[6:7], v[80:81] op_sel_hi:[1,0,1]
	v_pk_fma_f32 v[134:135], v[134:135], s[6:7], v[82:83] op_sel_hi:[1,0,1]
	s_waitcnt vmcnt(11)
	v_pk_fma_f32 v[136:137], v[136:137], s[6:7], v[76:77] op_sel_hi:[1,0,1]
	v_pk_fma_f32 v[138:139], v[138:139], s[6:7], v[78:79] op_sel_hi:[1,0,1]
	s_waitcnt vmcnt(10)
	v_pk_fma_f32 v[140:141], v[140:141], s[6:7], v[72:73] op_sel_hi:[1,0,1]
	v_pk_fma_f32 v[142:143], v[142:143], s[6:7], v[74:75] op_sel_hi:[1,0,1]
	s_waitcnt vmcnt(9)
	v_pk_fma_f32 v[144:145], v[144:145], s[6:7], v[60:61] op_sel_hi:[1,0,1]
	v_pk_fma_f32 v[146:147], v[146:147], s[6:7], v[62:63] op_sel_hi:[1,0,1]
	s_waitcnt vmcnt(8)
	v_pk_fma_f32 v[148:149], v[148:149], s[6:7], v[28:29] op_sel_hi:[1,0,1]
	v_pk_fma_f32 v[150:151], v[150:151], s[6:7], v[30:31] op_sel_hi:[1,0,1]
	s_waitcnt vmcnt(7)
	v_pk_fma_f32 v[20:21], v[20:21], s[6:7], v[64:65] op_sel_hi:[1,0,1]
	v_pk_fma_f32 v[22:23], v[22:23], s[6:7], v[66:67] op_sel_hi:[1,0,1]
	s_waitcnt vmcnt(6)
	v_pk_fma_f32 v[24:25], v[24:25], s[6:7], v[36:37] op_sel_hi:[1,0,1]
	v_pk_fma_f32 v[26:27], v[26:27], s[6:7], v[38:39] op_sel_hi:[1,0,1]
	s_waitcnt vmcnt(5)
	v_pk_fma_f32 v[40:41], v[40:41], s[6:7], v[32:33] op_sel_hi:[1,0,1]
	v_pk_fma_f32 v[42:43], v[42:43], s[6:7], v[34:35] op_sel_hi:[1,0,1]
	s_waitcnt vmcnt(4)
	v_pk_fma_f32 v[44:45], v[44:45], s[6:7], v[16:17] op_sel_hi:[1,0,1]
	v_pk_fma_f32 v[46:47], v[46:47], s[6:7], v[18:19] op_sel_hi:[1,0,1]
	s_waitcnt vmcnt(3)
	v_pk_fma_f32 v[48:49], v[48:49], s[6:7], v[12:13] op_sel_hi:[1,0,1]
	v_pk_fma_f32 v[50:51], v[50:51], s[6:7], v[14:15] op_sel_hi:[1,0,1]
	s_waitcnt vmcnt(2)
	v_pk_fma_f32 v[52:53], v[52:53], s[6:7], v[8:9] op_sel_hi:[1,0,1]
	v_pk_fma_f32 v[54:55], v[54:55], s[6:7], v[10:11] op_sel_hi:[1,0,1]
	s_waitcnt vmcnt(1)
	v_pk_fma_f32 v[56:57], v[56:57], s[6:7], v[4:5] op_sel_hi:[1,0,1]
	v_pk_fma_f32 v[58:59], v[58:59], s[6:7], v[6:7] op_sel_hi:[1,0,1]
	s_waitcnt vmcnt(0)
	v_pk_fma_f32 v[68:69], v[68:69], s[6:7], v[0:1] op_sel_hi:[1,0,1]
	v_pk_fma_f32 v[70:71], v[70:71], s[6:7], v[2:3] op_sel_hi:[1,0,1]
	global_store_dwordx4 v[160:161], v[120:123], off
	global_store_dwordx4 v[160:161], v[124:127], off offset:64
	global_store_dwordx4 v[160:161], v[128:131], off offset:128
	global_store_dwordx4 v[160:161], v[132:135], off offset:192
	global_store_dwordx4 v[162:163], v[136:139], off
	global_store_dwordx4 v[162:163], v[140:143], off offset:64
	global_store_dwordx4 v[162:163], v[144:147], off offset:128
	global_store_dwordx4 v[162:163], v[148:151], off offset:192
	global_store_dwordx4 v[164:165], v[20:23], off
	global_store_dwordx4 v[164:165], v[24:27], off offset:64
	global_store_dwordx4 v[164:165], v[40:43], off offset:128
	global_store_dwordx4 v[164:165], v[44:47], off offset:192
	global_store_dwordx4 v[166:167], v[48:51], off
	global_store_dwordx4 v[166:167], v[52:55], off offset:64
	global_store_dwordx4 v[166:167], v[56:59], off offset:128
	global_store_dwordx4 v[166:167], v[68:71], off offset:192
	s_add_i32 s7, s7, s3
	s_cmpk_lt_u32 s7, 0x100
	s_cbranch_scc1 .LBB0_798

.LBB0_889:
	s_lshr_b32 s6, s8, 1
	s_and_b32 s6, s6, 0xf8
	s_or_b32 s6, s6, s2
	s_lshl_b32 s12, s6, 7
	s_lshl_b32 s6, s8, 7
	v_or_b32_e32 v0, s12, v107
	s_and_b32 s13, s6, 0x780
	v_lshlrev_b32_e32 v96, 10, v0
	v_lshl_add_u64 v[102:103], v[98:99], 0, v[96:97]
	v_or_b32_e32 v0, s13, v107
	v_lshlrev_b32_e32 v96, 10, v0
	v_lshl_add_u64 v[104:105], v[100:101], 0, v[96:97]
	v_and_b32_e32 v181, 7, v106
	v_bfe_u32 v180, v106, 3, 3
	v_xor_b32_e32 v180, v181, v180
	v_sub_u32_e32 v180, v180, v181
	v_lshlrev_b32_e32 v180, 4, v180
	v_ashrrev_i32_e32 v181, 31, v180
	v_lshrrev_b32_e32 v186, 6, v106
	v_mov_b32_e32 v187, 0x110
	v_lshl_add_u32 v186, v186, 10, v187
	v_lshl_add_u64 v[188:189], v[102:103], 0, v[180:181]
	v_lshl_add_u64 v[196:197], v[104:105], 0, v[180:181]
	v_readfirstlane_b32 s16, v186
	v_add_co_u32_e32 v190, vcc, s9, v188
	v_addc_co_u32_e32 v191, vcc, 0, v189, vcc
	v_add_co_u32_e32 v192, vcc, s10, v188
	v_addc_co_u32_e32 v193, vcc, 0, v189, vcc
	v_add_co_u32_e32 v194, vcc, s11, v188
	v_addc_co_u32_e32 v195, vcc, 0, v189, vcc
	v_add_co_u32_e32 v198, vcc, s9, v196
	v_addc_co_u32_e32 v199, vcc, 0, v197, vcc
	v_add_co_u32_e32 v200, vcc, s10, v196
	v_addc_co_u32_e32 v201, vcc, 0, v197, vcc
	v_add_co_u32_e32 v202, vcc, s11, v196
	v_addc_co_u32_e32 v203, vcc, 0, v197, vcc
	v_mov_b32_e32 v28, 0
	v_mov_b32_e32 v29, v97
	v_mov_b32_e32 v30, v97
	v_mov_b32_e32 v31, v97
	v_mov_b32_e32 v36, 0
	v_mov_b32_e32 v37, v97
	v_mov_b32_e32 v38, v97
	v_mov_b32_e32 v39, v97
	v_mov_b32_e32 v40, 0
	v_mov_b32_e32 v41, v97
	v_mov_b32_e32 v42, v97
	v_mov_b32_e32 v43, v97
	v_mov_b32_e32 v60, 0
	v_mov_b32_e32 v61, v97
	v_mov_b32_e32 v62, v97
	v_mov_b32_e32 v63, v97
	v_mov_b32_e32 v80, 0
	v_mov_b32_e32 v81, v97
	v_mov_b32_e32 v82, v97
	v_mov_b32_e32 v83, v97
	v_mov_b32_e32 v84, 0
	v_mov_b32_e32 v85, v97
	v_mov_b32_e32 v86, v97
	v_mov_b32_e32 v87, v97
	v_mov_b32_e32 v88, 0
	v_mov_b32_e32 v89, v97
	v_mov_b32_e32 v90, v97
	v_mov_b32_e32 v91, v97
	v_mov_b32_e32 v92, 0
	v_mov_b32_e32 v93, v97
	v_mov_b32_e32 v94, v97
	v_mov_b32_e32 v95, v97
	v_mov_b32_e32 v32, 0
	v_mov_b32_e32 v33, v97
	v_mov_b32_e32 v34, v97
	v_mov_b32_e32 v35, v97
	v_mov_b32_e32 v24, 0
	v_mov_b32_e32 v25, v97
	v_mov_b32_e32 v26, v97
	v_mov_b32_e32 v27, v97
	v_mov_b32_e32 v20, 0
	v_mov_b32_e32 v21, v97
	v_mov_b32_e32 v22, v97
	v_mov_b32_e32 v23, v97
	v_mov_b32_e32 v16, 0
	v_mov_b32_e32 v17, v97
	v_mov_b32_e32 v18, v97
	v_mov_b32_e32 v19, v97
	v_mov_b32_e32 v12, 0
	v_mov_b32_e32 v13, v97
	v_mov_b32_e32 v14, v97
	v_mov_b32_e32 v15, v97
	v_mov_b32_e32 v8, 0
	v_mov_b32_e32 v9, v97
	v_mov_b32_e32 v10, v97
	v_mov_b32_e32 v11, v97
	v_mov_b32_e32 v4, 0
	v_mov_b32_e32 v5, v97
	v_mov_b32_e32 v6, v97
	v_mov_b32_e32 v7, v97
	v_mov_b32_e32 v0, 0
	v_mov_b32_e32 v1, v97
	v_mov_b32_e32 v2, v97
	v_mov_b32_e32 v3, v97
	s_add_u32 m0, s16, 0x0
	s_nop 0
	global_load_lds_dwordx4 v[188:189], off
	s_add_u32 m0, s16, 0x1000
	s_nop 0
	global_load_lds_dwordx4 v[190:191], off
	s_add_u32 m0, s16, 0x2000
	s_nop 0
	global_load_lds_dwordx4 v[192:193], off
	s_add_u32 m0, s16, 0x3000
	s_nop 0
	global_load_lds_dwordx4 v[194:195], off
	s_add_u32 m0, s16, 0x4000
	s_nop 0
	global_load_lds_dwordx4 v[196:197], off
	s_add_u32 m0, s16, 0x5000
	s_nop 0
	global_load_lds_dwordx4 v[198:199], off
	s_add_u32 m0, s16, 0x6000
	s_nop 0
	global_load_lds_dwordx4 v[200:201], off
	s_add_u32 m0, s16, 0x7000
	s_nop 0
	global_load_lds_dwordx4 v[202:203], off
	s_mov_b32 s15, 0
	s_mov_b32 s14, -2
	s_waitcnt vmcnt(0)
	s_barrier
.Lglds_28042:
	s_add_i32 s6, s15, 0x40
	s_lshl_b32 s6, s6, 1
	s_add_u32 m0, s16, 0x8000
	v_lshl_add_u64 v[204:205], v[188:189], 0, s[6:7]
	global_load_lds_dwordx4 v[204:205], off
	s_add_u32 m0, s16, 0x9000
	v_lshl_add_u64 v[206:207], v[190:191], 0, s[6:7]
	global_load_lds_dwordx4 v[206:207], off
	s_add_u32 m0, s16, 0xa000
	v_lshl_add_u64 v[204:205], v[192:193], 0, s[6:7]
	global_load_lds_dwordx4 v[204:205], off
	s_add_u32 m0, s16, 0xb000
	v_lshl_add_u64 v[206:207], v[194:195], 0, s[6:7]
	global_load_lds_dwordx4 v[206:207], off
	s_add_u32 m0, s16, 0xc000
	v_lshl_add_u64 v[204:205], v[196:197], 0, s[6:7]
	global_load_lds_dwordx4 v[204:205], off
	s_add_u32 m0, s16, 0xd000
	v_lshl_add_u64 v[206:207], v[198:199], 0, s[6:7]
	global_load_lds_dwordx4 v[206:207], off
	s_add_u32 m0, s16, 0xe000
	v_lshl_add_u64 v[204:205], v[200:201], 0, s[6:7]
	global_load_lds_dwordx4 v[204:205], off
	s_add_u32 m0, s16, 0xf000
	v_lshl_add_u64 v[206:207], v[202:203], 0, s[6:7]
	global_load_lds_dwordx4 v[206:207], off
	s_setprio 1
	ds_read_b128 v[152:155], v111 offset:16384
	ds_read_b128 v[156:159], v111 offset:18432
	ds_read_b128 v[160:163], v109
	ds_read_b128 v[164:167], v109 offset:2048
	ds_read_b128 v[168:171], v111 offset:20480
	ds_read_b128 v[172:175], v112 offset:16384
	s_waitcnt lgkmcnt(3)
	v_mfma_i32_16x16x64_i8 v[92:95], v[152:155], v[160:163], v[92:95]
	v_mfma_i32_16x16x64_i8 v[88:91], v[156:159], v[160:163], v[88:91]
	s_waitcnt lgkmcnt(1)
	v_mfma_i32_16x16x64_i8 v[84:87], v[168:171], v[160:163], v[84:87]
	s_waitcnt lgkmcnt(0)
	v_mfma_i32_16x16x64_i8 v[80:83], v[172:175], v[160:163], v[80:83]
	v_mfma_i32_16x16x64_i8 v[60:63], v[152:155], v[164:167], v[60:63]
	v_mfma_i32_16x16x64_i8 v[40:43], v[156:159], v[164:167], v[40:43]
	v_mfma_i32_16x16x64_i8 v[36:39], v[168:171], v[164:167], v[36:39]
	v_mfma_i32_16x16x64_i8 v[28:31], v[172:175], v[164:167], v[28:31]
	ds_read_b128 v[160:163], v109 offset:4096
	ds_read_b128 v[164:167], v110
	s_waitcnt lgkmcnt(1)
	v_mfma_i32_16x16x64_i8 v[32:35], v[152:155], v[160:163], v[32:35]
	v_mfma_i32_16x16x64_i8 v[24:27], v[156:159], v[160:163], v[24:27]
	v_mfma_i32_16x16x64_i8 v[20:23], v[168:171], v[160:163], v[20:23]
	v_mfma_i32_16x16x64_i8 v[16:19], v[172:175], v[160:163], v[16:19]
	s_waitcnt lgkmcnt(0)
	v_mfma_i32_16x16x64_i8 v[12:15], v[152:155], v[164:167], v[12:15]
	ds_read_b128 v[152:155], v115 offset:16384
	v_mfma_i32_16x16x64_i8 v[8:11], v[156:159], v[164:167], v[8:11]
	v_mfma_i32_16x16x64_i8 v[4:7], v[168:171], v[164:167], v[4:7]
	v_mfma_i32_16x16x64_i8 v[0:3], v[172:175], v[164:167], v[0:3]
	ds_read_b128 v[156:159], v115 offset:18432
	ds_read_b128 v[160:163], v113
	ds_read_b128 v[164:167], v113 offset:2048
	ds_read_b128 v[168:171], v115 offset:20480
	ds_read_b128 v[172:175], v116 offset:16384
	s_waitcnt lgkmcnt(3)
	v_mfma_i32_16x16x64_i8 v[92:95], v[152:155], v[160:163], v[92:95]
	v_mfma_i32_16x16x64_i8 v[88:91], v[156:159], v[160:163], v[88:91]
	s_waitcnt lgkmcnt(1)
	v_mfma_i32_16x16x64_i8 v[84:87], v[168:171], v[160:163], v[84:87]
	s_waitcnt lgkmcnt(0)
	v_mfma_i32_16x16x64_i8 v[80:83], v[172:175], v[160:163], v[80:83]
	v_mfma_i32_16x16x64_i8 v[60:63], v[152:155], v[164:167], v[60:63]
	v_mfma_i32_16x16x64_i8 v[40:43], v[156:159], v[164:167], v[40:43]
	v_mfma_i32_16x16x64_i8 v[36:39], v[168:171], v[164:167], v[36:39]
	v_mfma_i32_16x16x64_i8 v[28:31], v[172:175], v[164:167], v[28:31]
	ds_read_b128 v[160:163], v113 offset:4096
	ds_read_b128 v[164:167], v114
	s_waitcnt lgkmcnt(1)
	v_mfma_i32_16x16x64_i8 v[32:35], v[152:155], v[160:163], v[32:35]
	v_mfma_i32_16x16x64_i8 v[24:27], v[156:159], v[160:163], v[24:27]
	v_mfma_i32_16x16x64_i8 v[20:23], v[168:171], v[160:163], v[20:23]
	v_mfma_i32_16x16x64_i8 v[16:19], v[172:175], v[160:163], v[16:19]
	s_waitcnt lgkmcnt(0)
	v_mfma_i32_16x16x64_i8 v[12:15], v[152:155], v[164:167], v[12:15]
	v_mfma_i32_16x16x64_i8 v[8:11], v[156:159], v[164:167], v[8:11]
	v_mfma_i32_16x16x64_i8 v[4:7], v[168:171], v[164:167], v[4:7]
	v_mfma_i32_16x16x64_i8 v[0:3], v[172:175], v[164:167], v[0:3]
	s_setprio 0
	s_waitcnt vmcnt(0)
	s_barrier
	s_add_i32 s6, s15, 0x80
	s_min_u32 s6, s6, 0x1c0
	s_lshl_b32 s6, s6, 1
	s_add_u32 m0, s16, 0x0
	v_lshl_add_u64 v[204:205], v[188:189], 0, s[6:7]
	global_load_lds_dwordx4 v[204:205], off
	s_add_u32 m0, s16, 0x1000
	v_lshl_add_u64 v[206:207], v[190:191], 0, s[6:7]
	global_load_lds_dwordx4 v[206:207], off
	s_add_u32 m0, s16, 0x2000
	v_lshl_add_u64 v[204:205], v[192:193], 0, s[6:7]
	global_load_lds_dwordx4 v[204:205], off
	s_add_u32 m0, s16, 0x3000
	v_lshl_add_u64 v[206:207], v[194:195], 0, s[6:7]
	global_load_lds_dwordx4 v[206:207], off
	s_add_u32 m0, s16, 0x4000
	v_lshl_add_u64 v[204:205], v[196:197], 0, s[6:7]
	global_load_lds_dwordx4 v[204:205], off
	s_add_u32 m0, s16, 0x5000
	v_lshl_add_u64 v[206:207], v[198:199], 0, s[6:7]
	global_load_lds_dwordx4 v[206:207], off
	s_add_u32 m0, s16, 0x6000
	v_lshl_add_u64 v[204:205], v[200:201], 0, s[6:7]
	global_load_lds_dwordx4 v[204:205], off
	s_add_u32 m0, s16, 0x7000
	v_lshl_add_u64 v[206:207], v[202:203], 0, s[6:7]
	global_load_lds_dwordx4 v[206:207], off
	s_setprio 1
	ds_read_b128 v[152:155], v111 offset:49152
	ds_read_b128 v[156:159], v111 offset:51200
	ds_read_b128 v[160:163], v109 offset:32768
	ds_read_b128 v[164:167], v109 offset:34816
	ds_read_b128 v[168:171], v111 offset:53248
	ds_read_b128 v[172:175], v112 offset:49152
	s_waitcnt lgkmcnt(3)
	v_mfma_i32_16x16x64_i8 v[92:95], v[152:155], v[160:163], v[92:95]
	v_mfma_i32_16x16x64_i8 v[88:91], v[156:159], v[160:163], v[88:91]
	s_waitcnt lgkmcnt(1)
	v_mfma_i32_16x16x64_i8 v[84:87], v[168:171], v[160:163], v[84:87]
	s_waitcnt lgkmcnt(0)
	v_mfma_i32_16x16x64_i8 v[80:83], v[172:175], v[160:163], v[80:83]
	v_mfma_i32_16x16x64_i8 v[60:63], v[152:155], v[164:167], v[60:63]
	v_mfma_i32_16x16x64_i8 v[40:43], v[156:159], v[164:167], v[40:43]
	v_mfma_i32_16x16x64_i8 v[36:39], v[168:171], v[164:167], v[36:39]
	v_mfma_i32_16x16x64_i8 v[28:31], v[172:175], v[164:167], v[28:31]
	ds_read_b128 v[160:163], v109 offset:36864
	ds_read_b128 v[164:167], v110 offset:32768
	s_waitcnt lgkmcnt(1)
	v_mfma_i32_16x16x64_i8 v[32:35], v[152:155], v[160:163], v[32:35]
	v_mfma_i32_16x16x64_i8 v[24:27], v[156:159], v[160:163], v[24:27]
	v_mfma_i32_16x16x64_i8 v[20:23], v[168:171], v[160:163], v[20:23]
	v_mfma_i32_16x16x64_i8 v[16:19], v[172:175], v[160:163], v[16:19]
	s_waitcnt lgkmcnt(0)
	v_mfma_i32_16x16x64_i8 v[12:15], v[152:155], v[164:167], v[12:15]
	ds_read_b128 v[152:155], v115 offset:49152
	v_mfma_i32_16x16x64_i8 v[8:11], v[156:159], v[164:167], v[8:11]
	v_mfma_i32_16x16x64_i8 v[4:7], v[168:171], v[164:167], v[4:7]
	v_mfma_i32_16x16x64_i8 v[0:3], v[172:175], v[164:167], v[0:3]
	ds_read_b128 v[156:159], v115 offset:51200
	ds_read_b128 v[160:163], v113 offset:32768
	ds_read_b128 v[164:167], v113 offset:34816
	ds_read_b128 v[168:171], v115 offset:53248
	ds_read_b128 v[172:175], v116 offset:49152
	s_waitcnt lgkmcnt(3)
	v_mfma_i32_16x16x64_i8 v[92:95], v[152:155], v[160:163], v[92:95]
	v_mfma_i32_16x16x64_i8 v[88:91], v[156:159], v[160:163], v[88:91]
	s_waitcnt lgkmcnt(1)
	v_mfma_i32_16x16x64_i8 v[84:87], v[168:171], v[160:163], v[84:87]
	s_waitcnt lgkmcnt(0)
	v_mfma_i32_16x16x64_i8 v[80:83], v[172:175], v[160:163], v[80:83]
	v_mfma_i32_16x16x64_i8 v[60:63], v[152:155], v[164:167], v[60:63]
	v_mfma_i32_16x16x64_i8 v[40:43], v[156:159], v[164:167], v[40:43]
	v_mfma_i32_16x16x64_i8 v[36:39], v[168:171], v[164:167], v[36:39]
	v_mfma_i32_16x16x64_i8 v[28:31], v[172:175], v[164:167], v[28:31]
	ds_read_b128 v[160:163], v113 offset:36864
	ds_read_b128 v[164:167], v114 offset:32768
	s_waitcnt lgkmcnt(1)
	v_mfma_i32_16x16x64_i8 v[32:35], v[152:155], v[160:163], v[32:35]
	v_mfma_i32_16x16x64_i8 v[24:27], v[156:159], v[160:163], v[24:27]
	v_mfma_i32_16x16x64_i8 v[20:23], v[168:171], v[160:163], v[20:23]
	v_mfma_i32_16x16x64_i8 v[16:19], v[172:175], v[160:163], v[16:19]
	s_waitcnt lgkmcnt(0)
	v_mfma_i32_16x16x64_i8 v[12:15], v[152:155], v[164:167], v[12:15]
	v_mfma_i32_16x16x64_i8 v[8:11], v[156:159], v[164:167], v[8:11]
	v_mfma_i32_16x16x64_i8 v[4:7], v[168:171], v[164:167], v[4:7]
	v_mfma_i32_16x16x64_i8 v[0:3], v[172:175], v[164:167], v[0:3]
	s_setprio 0
	s_add_i32 s15, s15, 0x80
	s_add_i32 s14, s14, 2
	s_waitcnt vmcnt(0)
	s_barrier
	s_cmp_lt_u32 s14, 6
	s_cbranch_scc1 .Lglds_28042
	v_cvt_f32_i32_e32 v92, v92
	v_cvt_f32_i32_e32 v93, v93
	v_cvt_f32_i32_e32 v94, v94
	v_cvt_f32_i32_e32 v95, v95
	v_cvt_f32_i32_e32 v88, v88
	v_cvt_f32_i32_e32 v89, v89
	v_cvt_f32_i32_e32 v90, v90
	v_cvt_f32_i32_e32 v91, v91
	v_cvt_f32_i32_e32 v84, v84
	v_cvt_f32_i32_e32 v85, v85
	v_cvt_f32_i32_e32 v86, v86
	v_cvt_f32_i32_e32 v87, v87
	v_cvt_f32_i32_e32 v80, v80
	v_cvt_f32_i32_e32 v81, v81
	v_cvt_f32_i32_e32 v82, v82
	v_cvt_f32_i32_e32 v83, v83
	v_cvt_f32_i32_e32 v60, v60
	v_cvt_f32_i32_e32 v61, v61
	v_cvt_f32_i32_e32 v62, v62
	v_cvt_f32_i32_e32 v63, v63
	v_cvt_f32_i32_e32 v40, v40
	v_cvt_f32_i32_e32 v41, v41
	v_cvt_f32_i32_e32 v42, v42
	v_cvt_f32_i32_e32 v43, v43
	v_cvt_f32_i32_e32 v36, v36
	v_cvt_f32_i32_e32 v37, v37
	v_cvt_f32_i32_e32 v38, v38
	v_cvt_f32_i32_e32 v39, v39
	v_cvt_f32_i32_e32 v28, v28
	v_cvt_f32_i32_e32 v29, v29
	v_cvt_f32_i32_e32 v30, v30
	v_cvt_f32_i32_e32 v31, v31
	v_cvt_f32_i32_e32 v32, v32
	v_cvt_f32_i32_e32 v33, v33
	v_cvt_f32_i32_e32 v34, v34
	v_cvt_f32_i32_e32 v35, v35
	v_cvt_f32_i32_e32 v24, v24
	v_cvt_f32_i32_e32 v25, v25
	v_cvt_f32_i32_e32 v26, v26
	v_cvt_f32_i32_e32 v27, v27
	v_cvt_f32_i32_e32 v20, v20
	v_cvt_f32_i32_e32 v21, v21
	v_cvt_f32_i32_e32 v22, v22
	v_cvt_f32_i32_e32 v23, v23
	v_cvt_f32_i32_e32 v16, v16
	v_cvt_f32_i32_e32 v17, v17
	v_cvt_f32_i32_e32 v18, v18
	v_cvt_f32_i32_e32 v19, v19
	v_cvt_f32_i32_e32 v12, v12
	v_cvt_f32_i32_e32 v13, v13
	v_cvt_f32_i32_e32 v14, v14
	v_cvt_f32_i32_e32 v15, v15
	v_cvt_f32_i32_e32 v8, v8
	v_cvt_f32_i32_e32 v9, v9
	v_cvt_f32_i32_e32 v10, v10
	v_cvt_f32_i32_e32 v11, v11
	v_cvt_f32_i32_e32 v4, v4
	v_cvt_f32_i32_e32 v5, v5
	v_cvt_f32_i32_e32 v6, v6
	v_cvt_f32_i32_e32 v7, v7
	v_cvt_f32_i32_e32 v0, v0
	v_cvt_f32_i32_e32 v1, v1
	v_cvt_f32_i32_e32 v2, v2
	v_cvt_f32_i32_e32 v3, v3
	s_waitcnt vmcnt(0)
	v_add_u32_e32 v96, s12, v117
	v_or_b32_e32 v146, s13, v118
	v_lshl_add_u64 v[144:145], v[96:97], 2, s[68:69]
	v_lshlrev_b32_e32 v148, 2, v146
	global_load_dword v136, v[144:145], off
	global_load_dword v138, v[144:145], off offset:64
	global_load_dword v140, v[144:145], off offset:128
	global_load_dword v142, v[144:145], off offset:192
	global_load_dwordx4 v[120:123], v148, s[0:1]
	global_load_dwordx4 v[124:127], v148, s[0:1] offset:64
	global_load_dwordx4 v[128:131], v148, s[0:1] offset:128
	global_load_dwordx4 v[132:135], v148, s[0:1] offset:192
	v_lshlrev_b32_e32 v146, 1, v146
	v_mov_b32_e32 v147, v97
	v_lshlrev_b64 v[44:45], 12, v[96:97]
	v_lshl_add_u64 v[44:45], s[64:65], 0, v[44:45]
	v_lshl_add_u64 v[44:45], v[44:45], 0, v[146:147]
	v_or_b32_e32 v52, 16, v96
	v_mov_b32_e32 v53, v97
	v_lshlrev_b64 v[46:47], 12, v[52:53]
	v_lshl_add_u64 v[46:47], s[64:65], 0, v[46:47]
	v_lshl_add_u64 v[46:47], v[46:47], 0, v[146:147]
	v_or_b32_e32 v52, 32, v96
	v_mov_b32_e32 v53, v97
	v_lshlrev_b64 v[48:49], 12, v[52:53]
	v_lshl_add_u64 v[48:49], s[64:65], 0, v[48:49]
	v_lshl_add_u64 v[48:49], v[48:49], 0, v[146:147]
	v_or_b32_e32 v52, 48, v96
	v_mov_b32_e32 v53, v97
	v_lshlrev_b64 v[50:51], 12, v[52:53]
	v_lshl_add_u64 v[50:51], s[64:65], 0, v[50:51]
	v_lshl_add_u64 v[50:51], v[50:51], 0, v[146:147]
	s_waitcnt vmcnt(0)
	v_pk_mul_f32 v[92:93], v[136:137], v[92:93] op_sel_hi:[0,1]
	v_pk_mul_f32 v[94:95], v[136:137], v[94:95] op_sel_hi:[0,1]
	v_pk_mul_f32 v[92:93], v[120:121], v[92:93]
	v_pk_mul_f32 v[94:95], v[94:95], v[122:123]
	v_cvt_pk_bf16_f32 v92, v92, v93
	v_cvt_pk_bf16_f32 v93, v94, v95
	global_store_dwordx2 v[44:45], v[92:93], off
	v_pk_mul_f32 v[88:89], v[136:137], v[88:89] op_sel_hi:[0,1]
	v_pk_mul_f32 v[90:91], v[136:137], v[90:91] op_sel_hi:[0,1]
	v_pk_mul_f32 v[88:89], v[124:125], v[88:89]
	v_pk_mul_f32 v[90:91], v[90:91], v[126:127]
	v_cvt_pk_bf16_f32 v88, v88, v89
	v_cvt_pk_bf16_f32 v89, v90, v91
	global_store_dwordx2 v[44:45], v[88:89], off offset:32
	v_pk_mul_f32 v[84:85], v[136:137], v[84:85] op_sel_hi:[0,1]
	v_pk_mul_f32 v[86:87], v[136:137], v[86:87] op_sel_hi:[0,1]
	v_pk_mul_f32 v[84:85], v[128:129], v[84:85]
	v_pk_mul_f32 v[86:87], v[86:87], v[130:131]
	v_cvt_pk_bf16_f32 v84, v84, v85
	v_cvt_pk_bf16_f32 v85, v86, v87
	global_store_dwordx2 v[44:45], v[84:85], off offset:64
	v_pk_mul_f32 v[80:81], v[136:137], v[80:81] op_sel_hi:[0,1]
	v_pk_mul_f32 v[82:83], v[136:137], v[82:83] op_sel_hi:[0,1]
	v_pk_mul_f32 v[80:81], v[132:133], v[80:81]
	v_pk_mul_f32 v[82:83], v[82:83], v[134:135]
	v_cvt_pk_bf16_f32 v80, v80, v81
	v_cvt_pk_bf16_f32 v81, v82, v83
	global_store_dwordx2 v[44:45], v[80:81], off offset:96
	v_pk_mul_f32 v[60:61], v[138:139], v[60:61] op_sel_hi:[0,1]
	v_pk_mul_f32 v[62:63], v[138:139], v[62:63] op_sel_hi:[0,1]
	v_pk_mul_f32 v[60:61], v[120:121], v[60:61]
	v_pk_mul_f32 v[62:63], v[62:63], v[122:123]
	v_cvt_pk_bf16_f32 v60, v60, v61
	v_cvt_pk_bf16_f32 v61, v62, v63
	global_store_dwordx2 v[46:47], v[60:61], off
	v_pk_mul_f32 v[40:41], v[138:139], v[40:41] op_sel_hi:[0,1]
	v_pk_mul_f32 v[42:43], v[138:139], v[42:43] op_sel_hi:[0,1]
	v_pk_mul_f32 v[40:41], v[124:125], v[40:41]
	v_pk_mul_f32 v[42:43], v[42:43], v[126:127]
	v_cvt_pk_bf16_f32 v40, v40, v41
	v_cvt_pk_bf16_f32 v41, v42, v43
	global_store_dwordx2 v[46:47], v[40:41], off offset:32
	v_pk_mul_f32 v[36:37], v[138:139], v[36:37] op_sel_hi:[0,1]
	v_pk_mul_f32 v[38:39], v[138:139], v[38:39] op_sel_hi:[0,1]
	v_pk_mul_f32 v[36:37], v[128:129], v[36:37]
	v_pk_mul_f32 v[38:39], v[38:39], v[130:131]
	v_cvt_pk_bf16_f32 v36, v36, v37
	v_cvt_pk_bf16_f32 v37, v38, v39
	global_store_dwordx2 v[46:47], v[36:37], off offset:64
	v_pk_mul_f32 v[28:29], v[138:139], v[28:29] op_sel_hi:[0,1]
	v_pk_mul_f32 v[30:31], v[138:139], v[30:31] op_sel_hi:[0,1]
	v_pk_mul_f32 v[28:29], v[132:133], v[28:29]
	v_pk_mul_f32 v[30:31], v[30:31], v[134:135]
	v_cvt_pk_bf16_f32 v28, v28, v29
	v_cvt_pk_bf16_f32 v29, v30, v31
	global_store_dwordx2 v[46:47], v[28:29], off offset:96
	v_pk_mul_f32 v[32:33], v[140:141], v[32:33] op_sel_hi:[0,1]
	v_pk_mul_f32 v[34:35], v[140:141], v[34:35] op_sel_hi:[0,1]
	v_pk_mul_f32 v[32:33], v[120:121], v[32:33]
	v_pk_mul_f32 v[34:35], v[34:35], v[122:123]
	v_cvt_pk_bf16_f32 v32, v32, v33
	v_cvt_pk_bf16_f32 v33, v34, v35
	global_store_dwordx2 v[48:49], v[32:33], off
	v_pk_mul_f32 v[24:25], v[140:141], v[24:25] op_sel_hi:[0,1]
	v_pk_mul_f32 v[26:27], v[140:141], v[26:27] op_sel_hi:[0,1]
	v_pk_mul_f32 v[24:25], v[124:125], v[24:25]
	v_pk_mul_f32 v[26:27], v[26:27], v[126:127]
	v_cvt_pk_bf16_f32 v24, v24, v25
	v_cvt_pk_bf16_f32 v25, v26, v27
	global_store_dwordx2 v[48:49], v[24:25], off offset:32
	v_pk_mul_f32 v[20:21], v[140:141], v[20:21] op_sel_hi:[0,1]
	v_pk_mul_f32 v[22:23], v[140:141], v[22:23] op_sel_hi:[0,1]
	v_pk_mul_f32 v[20:21], v[128:129], v[20:21]
	v_pk_mul_f32 v[22:23], v[22:23], v[130:131]
	v_cvt_pk_bf16_f32 v20, v20, v21
	v_cvt_pk_bf16_f32 v21, v22, v23
	global_store_dwordx2 v[48:49], v[20:21], off offset:64
	v_pk_mul_f32 v[16:17], v[140:141], v[16:17] op_sel_hi:[0,1]
	v_pk_mul_f32 v[18:19], v[140:141], v[18:19] op_sel_hi:[0,1]
	v_pk_mul_f32 v[16:17], v[132:133], v[16:17]
	v_pk_mul_f32 v[18:19], v[18:19], v[134:135]
	v_cvt_pk_bf16_f32 v16, v16, v17
	v_cvt_pk_bf16_f32 v17, v18, v19
	global_store_dwordx2 v[48:49], v[16:17], off offset:96
	v_pk_mul_f32 v[12:13], v[142:143], v[12:13] op_sel_hi:[0,1]
	v_pk_mul_f32 v[14:15], v[142:143], v[14:15] op_sel_hi:[0,1]
	v_pk_mul_f32 v[12:13], v[120:121], v[12:13]
	v_pk_mul_f32 v[14:15], v[14:15], v[122:123]
	v_cvt_pk_bf16_f32 v12, v12, v13
	v_cvt_pk_bf16_f32 v13, v14, v15
	global_store_dwordx2 v[50:51], v[12:13], off
	v_pk_mul_f32 v[8:9], v[142:143], v[8:9] op_sel_hi:[0,1]
	v_pk_mul_f32 v[10:11], v[142:143], v[10:11] op_sel_hi:[0,1]
	v_pk_mul_f32 v[8:9], v[124:125], v[8:9]
	v_pk_mul_f32 v[10:11], v[10:11], v[126:127]
	v_cvt_pk_bf16_f32 v8, v8, v9
	v_cvt_pk_bf16_f32 v9, v10, v11
	global_store_dwordx2 v[50:51], v[8:9], off offset:32
	v_pk_mul_f32 v[4:5], v[142:143], v[4:5] op_sel_hi:[0,1]
	v_pk_mul_f32 v[6:7], v[142:143], v[6:7] op_sel_hi:[0,1]
	v_pk_mul_f32 v[4:5], v[128:129], v[4:5]
	v_pk_mul_f32 v[6:7], v[6:7], v[130:131]
	v_cvt_pk_bf16_f32 v4, v4, v5
	v_cvt_pk_bf16_f32 v5, v6, v7
	global_store_dwordx2 v[50:51], v[4:5], off offset:64
	v_pk_mul_f32 v[0:1], v[142:143], v[0:1] op_sel_hi:[0,1]
	v_pk_mul_f32 v[2:3], v[142:143], v[2:3] op_sel_hi:[0,1]
	v_pk_mul_f32 v[0:1], v[132:133], v[0:1]
	v_pk_mul_f32 v[2:3], v[2:3], v[134:135]
	v_cvt_pk_bf16_f32 v0, v0, v1
	v_cvt_pk_bf16_f32 v1, v2, v3
	global_store_dwordx2 v[50:51], v[0:1], off offset:96
	s_add_i32 s8, s8, s3
	s_cmpk_lt_u32 s8, 0x200
	s_cbranch_scc1 .LBB0_889
